# v32 with the conversion's f32 weight loads marked sc0 sc1 nt (system-scope streaming) instead of nt
# speedup vs baseline: 1.0041x; 1.0041x over previous
.LBB0_1022:
	s_ashr_i32 s11, s10, 31
	s_lshr_b32 s11, s11, 27
	s_add_i32 s11, s10, s11
	s_ashr_i32 s11, s11, 5
	s_lshl_b32 s14, s11, 6
	s_lshl_b32 s11, s11, 10
	s_andn2_b64 vcc, exec, s[6:7]
	s_sub_i32 s11, 0, s11
	s_cbranch_vccnz .LBB0_1024
	s_add_i32 s18, s9, s11
	v_or_b32_e32 v18, s14, v20
	s_ashr_i32 s19, s18, 31
	v_ashrrev_i32_e32 v19, 31, v18
	v_or_b32_e32 v14, 8, v18
	v_or_b32_e32 v26, 16, v18
	v_lshl_add_u64 v[46:47], s[18:19], 2, v[2:3]
	v_lshlrev_b64 v[6:7], 12, v[18:19]
	v_ashrrev_i32_e32 v15, 31, v14
	v_ashrrev_i32_e32 v27, 31, v26
	v_lshl_add_u64 v[6:7], v[46:47], 0, v[6:7]
	v_lshlrev_b64 v[14:15], 12, v[14:15]
	v_lshlrev_b64 v[26:27], 12, v[26:27]
	v_or_b32_e32 v30, 24, v18
	global_load_dwordx4 v[6:9], v[6:7], off sc0 sc1 nt
	v_lshl_add_u64 v[14:15], v[46:47], 0, v[14:15]
	v_lshl_add_u64 v[26:27], v[46:47], 0, v[26:27]
	v_ashrrev_i32_e32 v31, 31, v30
	v_or_b32_e32 v34, 32, v18
	global_load_dwordx4 v[14:17], v[14:15], off sc0 sc1 nt
	v_lshlrev_b64 v[30:31], 12, v[30:31]
	global_load_dwordx4 v[26:29], v[26:27], off sc0 sc1 nt
	v_ashrrev_i32_e32 v35, 31, v34
	v_lshl_add_u64 v[30:31], v[46:47], 0, v[30:31]
	v_lshlrev_b64 v[34:35], 12, v[34:35]
	v_or_b32_e32 v38, 40, v18
	global_load_dwordx4 v[30:33], v[30:31], off sc0 sc1 nt
	v_lshl_add_u64 v[34:35], v[46:47], 0, v[34:35]
	v_ashrrev_i32_e32 v39, 31, v38
	global_load_dwordx4 v[34:37], v[34:35], off sc0 sc1 nt
	v_lshlrev_b64 v[38:39], 12, v[38:39]
	v_or_b32_e32 v42, 48, v18
	v_lshl_add_u64 v[38:39], v[46:47], 0, v[38:39]
	v_ashrrev_i32_e32 v43, 31, v42
	global_load_dwordx4 v[38:41], v[38:39], off sc0 sc1 nt
	v_lshlrev_b64 v[42:43], 12, v[42:43]
	v_or_b32_e32 v18, 56, v18
	v_lshl_add_u64 v[42:43], v[46:47], 0, v[42:43]
	v_ashrrev_i32_e32 v19, 31, v18
	global_load_dwordx4 v[42:45], v[42:43], off sc0 sc1 nt
	v_lshlrev_b64 v[18:19], 12, v[18:19]
	v_lshl_add_u64 v[18:19], v[46:47], 0, v[18:19]
	global_load_dwordx4 v[46:49], v[18:19], off sc0 sc1 nt
	v_add_u32_e32 v0, v21, v23
	s_ashr_i32 s15, s14, 31
	s_waitcnt vmcnt(7)
	ds_write2_b32 v22, v6, v7 offset1:1
	ds_write2_b32 v22, v8, v9 offset0:2 offset1:3
	v_add_u32_e32 v6, 0x420, v0
	s_waitcnt vmcnt(6)
	ds_write2_b32 v0, v14, v15 offset1:1
	ds_write2_b32 v0, v16, v17 offset0:2 offset1:3
	s_waitcnt vmcnt(5)
	ds_write2_b32 v6, v26, v27 offset1:1
	v_add_u32_e32 v6, 0x428, v0
	ds_write2_b32 v6, v28, v29 offset1:1
	v_add_u32_e32 v6, 0x840, v0
	v_add_u32_e32 v0, 0x848, v0
	s_waitcnt vmcnt(4)
	ds_write2_b32 v0, v32, v33 offset1:1
	v_add_u32_e32 v0, 0x1080, v22
	ds_write2_b32 v6, v30, v31 offset1:1
	s_waitcnt vmcnt(3)
	ds_write2_b32 v0, v34, v35 offset1:1
	v_add_u32_e32 v0, 0x1088, v22
	ds_write2_b32 v0, v36, v37 offset1:1
	v_add_u32_e32 v0, 0x14a0, v22
	v_lshl_add_u64 v[6:7], s[14:15], 1, v[4:5]
	s_waitcnt vmcnt(2)
	ds_write2_b32 v0, v38, v39 offset1:1
	v_add_u32_e32 v0, 0x14a8, v22
	ds_write2_b32 v0, v40, v41 offset1:1
	v_add_u32_e32 v0, 0x18c0, v22
	v_add_u32_e32 v38, s18, v20
	s_waitcnt vmcnt(1)
	ds_write2_b32 v0, v42, v43 offset1:1
	v_add_u32_e32 v0, 0x18c8, v22
	ds_write2_b32 v0, v44, v45 offset1:1
	v_add_u32_e32 v0, 0x1ce0, v22
	s_waitcnt vmcnt(0)
	ds_write2_b32 v0, v46, v47 offset1:1
	v_add_u32_e32 v0, 0x1ce8, v22
	ds_write2_b32 v0, v48, v49 offset1:1
	s_waitcnt lgkmcnt(0)
	ds_read2_b32 v[8:9], v24 offset0:33 offset1:41
	ds_read2_b32 v[18:19], v24 offset1:8
	ds_read2_b32 v[26:27], v24 offset0:66 offset1:74
	ds_read2_b32 v[28:29], v24 offset0:99 offset1:107
	ds_read2_b32 v[30:31], v24 offset0:132 offset1:140
	ds_read2_b32 v[32:33], v24 offset0:165 offset1:173
	ds_read2_b32 v[34:35], v24 offset0:198 offset1:206
	ds_read2_b32 v[36:37], v24 offset0:231 offset1:239
	v_ashrrev_i32_e32 v39, 31, v38
	v_lshlrev_b64 v[40:41], 13, v[38:39]
	s_waitcnt lgkmcnt(6)
	v_cvt_pk_bf16_f32 v14, v18, v8
	s_waitcnt lgkmcnt(4)
	v_cvt_pk_bf16_f32 v15, v26, v28
	s_waitcnt lgkmcnt(2)
	v_cvt_pk_bf16_f32 v16, v30, v32
	s_waitcnt lgkmcnt(0)
	v_cvt_pk_bf16_f32 v17, v34, v36
	v_lshl_add_u64 v[40:41], v[6:7], 0, v[40:41]
	v_add_u32_e32 v8, 8, v38
	global_store_dwordx4 v[40:41], v[14:17], off
	v_add_u32_e32 v40, 16, v38
	v_ashrrev_i32_e32 v41, 31, v40
	v_cvt_pk_bf16_f32 v14, v19, v9
	v_ashrrev_i32_e32 v9, 31, v8
	v_lshlrev_b64 v[8:9], 13, v[8:9]
	v_cvt_pk_bf16_f32 v15, v27, v29
	v_cvt_pk_bf16_f32 v16, v31, v33
	v_cvt_pk_bf16_f32 v17, v35, v37
	v_lshl_add_u64 v[8:9], v[6:7], 0, v[8:9]
	global_store_dwordx4 v[8:9], v[14:17], off
	ds_read2_b32 v[8:9], v24 offset0:49 offset1:57
	ds_read2_b32 v[18:19], v24 offset0:16 offset1:24
	ds_read2_b32 v[26:27], v24 offset0:82 offset1:90
	ds_read2_b32 v[28:29], v24 offset0:115 offset1:123
	ds_read2_b32 v[30:31], v24 offset0:148 offset1:156
	ds_read2_b32 v[32:33], v24 offset0:181 offset1:189
	ds_read2_b32 v[34:35], v24 offset0:214 offset1:222
	ds_read2_b32 v[36:37], v24 offset0:247 offset1:255
	v_lshlrev_b64 v[40:41], 13, v[40:41]
	s_waitcnt lgkmcnt(6)
	v_cvt_pk_bf16_f32 v14, v18, v8
	s_waitcnt lgkmcnt(4)
	v_cvt_pk_bf16_f32 v15, v26, v28
	s_waitcnt lgkmcnt(2)
	v_cvt_pk_bf16_f32 v16, v30, v32
	s_waitcnt lgkmcnt(0)
	v_cvt_pk_bf16_f32 v17, v34, v36
	v_lshl_add_u64 v[40:41], v[6:7], 0, v[40:41]
	v_add_u32_e32 v8, 24, v38
	global_store_dwordx4 v[40:41], v[14:17], off
	s_nop 1
	v_cvt_pk_bf16_f32 v14, v19, v9
	v_ashrrev_i32_e32 v9, 31, v8
	v_lshlrev_b64 v[8:9], 13, v[8:9]
	v_cvt_pk_bf16_f32 v15, v27, v29
	v_cvt_pk_bf16_f32 v16, v31, v33
	v_cvt_pk_bf16_f32 v17, v35, v37
	v_lshl_add_u64 v[6:7], v[6:7], 0, v[8:9]
	global_store_dwordx4 v[6:7], v[14:17], off
	s_waitcnt lgkmcnt(0)
	s_cbranch_execnz .LBB0_1021
	s_branch .LBB0_1020

.LBB0_1030:
	s_mul_hi_i32 s11, s10, 0x2aaaaaab
	s_lshr_b32 s12, s11, 31
	s_ashr_i32 s11, s11, 3
	s_add_i32 s11, s11, s12
	s_lshl_b32 s18, s11, 6
	s_andn2_b64 vcc, exec, s[14:15]
	s_mulk_i32 s11, 0xfa00
	s_cbranch_vccnz .LBB0_1032
	s_add_i32 s24, s9, s11
	v_or_b32_e32 v0, s18, v20
	s_ashr_i32 s25, s24, 31
	v_lshl_add_u64 v[18:19], s[24:25], 2, v[2:3]
	v_or_b32_e32 v11, 8, v0
	v_mad_i64_i32 v[6:7], s[12:13], v0, s76, v[18:19]
	v_mad_i64_i32 v[14:15], s[12:13], v11, s76, v[18:19]
	v_or_b32_e32 v11, 16, v0
	global_load_dwordx4 v[6:9], v[6:7], off sc0 sc1 nt
	v_mad_i64_i32 v[26:27], s[12:13], v11, s76, v[18:19]
	global_load_dwordx4 v[14:17], v[14:15], off sc0 sc1 nt
	v_or_b32_e32 v11, 24, v0
	global_load_dwordx4 v[26:29], v[26:27], off sc0 sc1 nt
	v_mad_i64_i32 v[30:31], s[12:13], v11, s76, v[18:19]
	v_or_b32_e32 v11, 32, v0
	global_load_dwordx4 v[30:33], v[30:31], off sc0 sc1 nt
	v_mad_i64_i32 v[34:35], s[12:13], v11, s76, v[18:19]
	global_load_dwordx4 v[34:37], v[34:35], off sc0 sc1 nt
	v_or_b32_e32 v11, 40, v0
	v_mad_i64_i32 v[38:39], s[12:13], v11, s76, v[18:19]
	global_load_dwordx4 v[38:41], v[38:39], off sc0 sc1 nt
	v_or_b32_e32 v11, 48, v0
	v_mad_i64_i32 v[42:43], s[12:13], v11, s76, v[18:19]
	global_load_dwordx4 v[42:45], v[42:43], off sc0 sc1 nt
	v_or_b32_e32 v0, 56, v0
	v_mad_i64_i32 v[18:19], s[12:13], v0, s76, v[18:19]
	global_load_dwordx4 v[46:49], v[18:19], off sc0 sc1 nt
	v_add_u32_e32 v0, v21, v23
	s_ashr_i32 s19, s18, 31
	s_waitcnt vmcnt(7)
	ds_write2_b32 v22, v6, v7 offset1:1
	ds_write2_b32 v22, v8, v9 offset0:2 offset1:3
	v_add_u32_e32 v6, 0x420, v0
	s_waitcnt vmcnt(6)
	ds_write2_b32 v0, v14, v15 offset1:1
	ds_write2_b32 v0, v16, v17 offset0:2 offset1:3
	v_add_u32_e32 v8, s24, v20
	s_waitcnt vmcnt(5)
	ds_write2_b32 v6, v26, v27 offset1:1
	v_add_u32_e32 v6, 0x428, v0
	ds_write2_b32 v6, v28, v29 offset1:1
	v_add_u32_e32 v6, 0x840, v0
	v_add_u32_e32 v0, 0x848, v0
	s_waitcnt vmcnt(4)
	ds_write2_b32 v0, v32, v33 offset1:1
	v_add_u32_e32 v0, 0x1080, v22
	s_waitcnt vmcnt(3)
	ds_write2_b32 v0, v34, v35 offset1:1
	v_add_u32_e32 v0, 0x1088, v22
	ds_write2_b32 v0, v36, v37 offset1:1
	v_add_u32_e32 v0, 0x14a0, v22
	s_waitcnt vmcnt(2)
	ds_write2_b32 v0, v38, v39 offset1:1
	v_add_u32_e32 v0, 0x14a8, v22
	ds_write2_b32 v0, v40, v41 offset1:1
	v_add_u32_e32 v0, 0x18c0, v22
	s_waitcnt vmcnt(1)
	ds_write2_b32 v0, v42, v43 offset1:1
	v_add_u32_e32 v0, 0x18c8, v22
	ds_write2_b32 v0, v44, v45 offset1:1
	v_add_u32_e32 v0, 0x1ce0, v22
	s_waitcnt vmcnt(0)
	ds_write2_b32 v0, v46, v47 offset1:1
	v_add_u32_e32 v0, 0x1ce8, v22
	ds_write2_b32 v6, v30, v31 offset1:1
	ds_write2_b32 v0, v48, v49 offset1:1
	s_waitcnt lgkmcnt(0)
	ds_read2_b32 v[18:19], v24 offset0:33 offset1:41
	ds_read2_b32 v[26:27], v24 offset1:8
	ds_read2_b32 v[28:29], v24 offset0:66 offset1:74
	ds_read2_b32 v[30:31], v24 offset0:99 offset1:107
	ds_read2_b32 v[32:33], v24 offset0:132 offset1:140
	ds_read2_b32 v[34:35], v24 offset0:165 offset1:173
	ds_read2_b32 v[36:37], v24 offset0:198 offset1:206
	ds_read2_b32 v[38:39], v24 offset0:231 offset1:239
	v_ashrrev_i32_e32 v9, 31, v8
	v_lshl_add_u64 v[6:7], s[18:19], 1, v[4:5]
	v_lshlrev_b64 v[40:41], 11, v[8:9]
	s_waitcnt lgkmcnt(6)
	v_cvt_pk_bf16_f32 v14, v26, v18
	s_waitcnt lgkmcnt(4)
	v_cvt_pk_bf16_f32 v15, v28, v30
	s_waitcnt lgkmcnt(2)
	v_cvt_pk_bf16_f32 v16, v32, v34
	s_waitcnt lgkmcnt(0)
	v_cvt_pk_bf16_f32 v17, v36, v38
	v_lshl_add_u64 v[40:41], v[6:7], 0, v[40:41]
	v_add_u32_e32 v18, 8, v8
	global_store_dwordx4 v[40:41], v[14:17], off
	v_add_u32_e32 v40, 16, v8
	v_ashrrev_i32_e32 v41, 31, v40
	v_cvt_pk_bf16_f32 v14, v27, v19
	v_ashrrev_i32_e32 v19, 31, v18
	v_lshlrev_b64 v[18:19], 11, v[18:19]
	v_cvt_pk_bf16_f32 v15, v29, v31
	v_cvt_pk_bf16_f32 v16, v33, v35
	v_cvt_pk_bf16_f32 v17, v37, v39
	v_lshl_add_u64 v[18:19], v[6:7], 0, v[18:19]
	global_store_dwordx4 v[18:19], v[14:17], off
	ds_read2_b32 v[18:19], v24 offset0:49 offset1:57
	ds_read2_b32 v[26:27], v24 offset0:16 offset1:24
	ds_read2_b32 v[28:29], v24 offset0:82 offset1:90
	ds_read2_b32 v[30:31], v24 offset0:115 offset1:123
	ds_read2_b32 v[32:33], v24 offset0:148 offset1:156
	ds_read2_b32 v[34:35], v24 offset0:181 offset1:189
	ds_read2_b32 v[36:37], v24 offset0:214 offset1:222
	ds_read2_b32 v[38:39], v24 offset0:247 offset1:255
	v_add_u32_e32 v8, 24, v8
	v_lshlrev_b64 v[40:41], 11, v[40:41]
	v_ashrrev_i32_e32 v9, 31, v8
	s_waitcnt lgkmcnt(6)
	v_cvt_pk_bf16_f32 v14, v26, v18
	s_waitcnt lgkmcnt(4)
	v_cvt_pk_bf16_f32 v15, v28, v30
	s_waitcnt lgkmcnt(2)
	v_cvt_pk_bf16_f32 v16, v32, v34
	s_waitcnt lgkmcnt(0)
	v_cvt_pk_bf16_f32 v17, v36, v38
	v_lshl_add_u64 v[40:41], v[6:7], 0, v[40:41]
	v_lshlrev_b64 v[8:9], 11, v[8:9]
	global_store_dwordx4 v[40:41], v[14:17], off
	v_lshl_add_u64 v[6:7], v[6:7], 0, v[8:9]
	s_nop 0
	v_cvt_pk_bf16_f32 v14, v27, v19
	v_cvt_pk_bf16_f32 v15, v29, v31
	v_cvt_pk_bf16_f32 v16, v33, v35
	v_cvt_pk_bf16_f32 v17, v37, v39
	global_store_dwordx4 v[6:7], v[14:17], off
	s_waitcnt lgkmcnt(0)
	s_cbranch_execnz .LBB0_1029
	s_branch .LBB0_1028

.LBB0_1039:
	s_ashr_i32 s11, s9, 31
	s_lshr_b32 s11, s11, 27
	s_add_i32 s11, s9, s11
	s_ashr_i32 s11, s11, 5
	s_lshl_b32 s18, s11, 6
	s_lshl_b32 s11, s11, 10
	s_andn2_b64 vcc, exec, s[14:15]
	s_sub_i32 s11, 0, s11
	s_cbranch_vccnz .LBB0_1041
	s_add_i32 s24, s10, s11
	v_or_b32_e32 v18, s18, v20
	s_ashr_i32 s25, s24, 31
	v_ashrrev_i32_e32 v19, 31, v18
	v_or_b32_e32 v14, 8, v18
	v_or_b32_e32 v26, 16, v18
	v_lshl_add_u64 v[46:47], s[24:25], 2, v[2:3]
	v_lshlrev_b64 v[6:7], 12, v[18:19]
	v_ashrrev_i32_e32 v15, 31, v14
	v_ashrrev_i32_e32 v27, 31, v26
	v_lshl_add_u64 v[6:7], v[46:47], 0, v[6:7]
	v_lshlrev_b64 v[14:15], 12, v[14:15]
	v_lshlrev_b64 v[26:27], 12, v[26:27]
	v_or_b32_e32 v30, 24, v18
	global_load_dwordx4 v[6:9], v[6:7], off sc0 sc1 nt
	v_lshl_add_u64 v[14:15], v[46:47], 0, v[14:15]
	v_lshl_add_u64 v[26:27], v[46:47], 0, v[26:27]
	v_ashrrev_i32_e32 v31, 31, v30
	v_or_b32_e32 v34, 32, v18
	global_load_dwordx4 v[14:17], v[14:15], off sc0 sc1 nt
	v_lshlrev_b64 v[30:31], 12, v[30:31]
	global_load_dwordx4 v[26:29], v[26:27], off sc0 sc1 nt
	v_ashrrev_i32_e32 v35, 31, v34
	v_lshl_add_u64 v[30:31], v[46:47], 0, v[30:31]
	v_lshlrev_b64 v[34:35], 12, v[34:35]
	v_or_b32_e32 v38, 40, v18
	global_load_dwordx4 v[30:33], v[30:31], off sc0 sc1 nt
	v_lshl_add_u64 v[34:35], v[46:47], 0, v[34:35]
	v_ashrrev_i32_e32 v39, 31, v38
	global_load_dwordx4 v[34:37], v[34:35], off sc0 sc1 nt
	v_lshlrev_b64 v[38:39], 12, v[38:39]
	v_or_b32_e32 v42, 48, v18
	v_lshl_add_u64 v[38:39], v[46:47], 0, v[38:39]
	v_ashrrev_i32_e32 v43, 31, v42
	global_load_dwordx4 v[38:41], v[38:39], off sc0 sc1 nt
	v_lshlrev_b64 v[42:43], 12, v[42:43]
	v_or_b32_e32 v18, 56, v18
	v_lshl_add_u64 v[42:43], v[46:47], 0, v[42:43]
	v_ashrrev_i32_e32 v19, 31, v18
	global_load_dwordx4 v[42:45], v[42:43], off sc0 sc1 nt
	v_lshlrev_b64 v[18:19], 12, v[18:19]
	v_lshl_add_u64 v[18:19], v[46:47], 0, v[18:19]
	global_load_dwordx4 v[46:49], v[18:19], off sc0 sc1 nt
	v_add_u32_e32 v0, v21, v23
	s_ashr_i32 s19, s18, 31
	s_waitcnt vmcnt(7)
	ds_write2_b32 v22, v6, v7 offset1:1
	ds_write2_b32 v22, v8, v9 offset0:2 offset1:3
	v_add_u32_e32 v6, 0x420, v0
	s_waitcnt vmcnt(6)
	ds_write2_b32 v0, v14, v15 offset1:1
	ds_write2_b32 v0, v16, v17 offset0:2 offset1:3
	s_waitcnt vmcnt(5)
	ds_write2_b32 v6, v26, v27 offset1:1
	v_add_u32_e32 v6, 0x428, v0
	ds_write2_b32 v6, v28, v29 offset1:1
	v_add_u32_e32 v6, 0x840, v0
	v_add_u32_e32 v0, 0x848, v0
	s_waitcnt vmcnt(4)
	ds_write2_b32 v0, v32, v33 offset1:1
	v_add_u32_e32 v0, 0x1080, v22
	ds_write2_b32 v6, v30, v31 offset1:1
	s_waitcnt vmcnt(3)
	ds_write2_b32 v0, v34, v35 offset1:1
	v_add_u32_e32 v0, 0x1088, v22
	ds_write2_b32 v0, v36, v37 offset1:1
	v_add_u32_e32 v0, 0x14a0, v22
	v_lshl_add_u64 v[6:7], s[18:19], 1, v[4:5]
	s_waitcnt vmcnt(2)
	ds_write2_b32 v0, v38, v39 offset1:1
	v_add_u32_e32 v0, 0x14a8, v22
	ds_write2_b32 v0, v40, v41 offset1:1
	v_add_u32_e32 v0, 0x18c0, v22
	v_add_u32_e32 v38, s24, v20
	s_waitcnt vmcnt(1)
	ds_write2_b32 v0, v42, v43 offset1:1
	v_add_u32_e32 v0, 0x18c8, v22
	ds_write2_b32 v0, v44, v45 offset1:1
	v_add_u32_e32 v0, 0x1ce0, v22
	s_waitcnt vmcnt(0)
	ds_write2_b32 v0, v46, v47 offset1:1
	v_add_u32_e32 v0, 0x1ce8, v22
	ds_write2_b32 v0, v48, v49 offset1:1
	s_waitcnt lgkmcnt(0)
	ds_read2_b32 v[8:9], v24 offset0:33 offset1:41
	ds_read2_b32 v[18:19], v24 offset1:8
	ds_read2_b32 v[26:27], v24 offset0:66 offset1:74
	ds_read2_b32 v[28:29], v24 offset0:99 offset1:107
	ds_read2_b32 v[30:31], v24 offset0:132 offset1:140
	ds_read2_b32 v[32:33], v24 offset0:165 offset1:173
	ds_read2_b32 v[34:35], v24 offset0:198 offset1:206
	ds_read2_b32 v[36:37], v24 offset0:231 offset1:239
	v_ashrrev_i32_e32 v39, 31, v38
	v_lshlrev_b64 v[40:41], 11, v[38:39]
	s_waitcnt lgkmcnt(6)
	v_cvt_pk_bf16_f32 v14, v18, v8
	s_waitcnt lgkmcnt(4)
	v_cvt_pk_bf16_f32 v15, v26, v28
	s_waitcnt lgkmcnt(2)
	v_cvt_pk_bf16_f32 v16, v30, v32
	s_waitcnt lgkmcnt(0)
	v_cvt_pk_bf16_f32 v17, v34, v36
	v_lshl_add_u64 v[40:41], v[6:7], 0, v[40:41]
	v_add_u32_e32 v8, 8, v38
	global_store_dwordx4 v[40:41], v[14:17], off
	v_add_u32_e32 v40, 16, v38
	v_ashrrev_i32_e32 v41, 31, v40
	v_cvt_pk_bf16_f32 v14, v19, v9
	v_ashrrev_i32_e32 v9, 31, v8
	v_lshlrev_b64 v[8:9], 11, v[8:9]
	v_cvt_pk_bf16_f32 v15, v27, v29
	v_cvt_pk_bf16_f32 v16, v31, v33
	v_cvt_pk_bf16_f32 v17, v35, v37
	v_lshl_add_u64 v[8:9], v[6:7], 0, v[8:9]
	global_store_dwordx4 v[8:9], v[14:17], off
	ds_read2_b32 v[8:9], v24 offset0:49 offset1:57
	ds_read2_b32 v[18:19], v24 offset0:16 offset1:24
	ds_read2_b32 v[26:27], v24 offset0:82 offset1:90
	ds_read2_b32 v[28:29], v24 offset0:115 offset1:123
	ds_read2_b32 v[30:31], v24 offset0:148 offset1:156
	ds_read2_b32 v[32:33], v24 offset0:181 offset1:189
	ds_read2_b32 v[34:35], v24 offset0:214 offset1:222
	ds_read2_b32 v[36:37], v24 offset0:247 offset1:255
	v_lshlrev_b64 v[40:41], 11, v[40:41]
	s_waitcnt lgkmcnt(6)
	v_cvt_pk_bf16_f32 v14, v18, v8
	s_waitcnt lgkmcnt(4)
	v_cvt_pk_bf16_f32 v15, v26, v28
	s_waitcnt lgkmcnt(2)
	v_cvt_pk_bf16_f32 v16, v30, v32
	s_waitcnt lgkmcnt(0)
	v_cvt_pk_bf16_f32 v17, v34, v36
	v_lshl_add_u64 v[40:41], v[6:7], 0, v[40:41]
	v_add_u32_e32 v8, 24, v38
	global_store_dwordx4 v[40:41], v[14:17], off
	s_nop 1
	v_cvt_pk_bf16_f32 v14, v19, v9
	v_ashrrev_i32_e32 v9, 31, v8
	v_lshlrev_b64 v[8:9], 11, v[8:9]
	v_cvt_pk_bf16_f32 v15, v27, v29
	v_cvt_pk_bf16_f32 v16, v31, v33
	v_cvt_pk_bf16_f32 v17, v35, v37
	v_lshl_add_u64 v[6:7], v[6:7], 0, v[8:9]
	global_store_dwordx4 v[6:7], v[14:17], off
	s_waitcnt lgkmcnt(0)
	s_cbranch_execnz .LBB0_1038
	s_branch .LBB0_1037

.LBB0_1050:
	s_ashr_i32 s12, s11, 31
	s_lshr_b32 s12, s12, 27
	s_add_i32 s12, s11, s12
	s_ashr_i32 s12, s12, 5
	s_lshl_b32 s18, s12, 6
	s_lshl_b32 s12, s12, 10
	s_andn2_b64 vcc, exec, s[14:15]
	s_sub_i32 s12, 0, s12
	s_cbranch_vccnz .LBB0_1052
	s_add_i32 s24, s10, s12
	v_or_b32_e32 v14, s18, v20
	s_ashr_i32 s25, s24, 31
	v_ashrrev_i32_e32 v15, 31, v14
	v_lshl_add_u64 v[18:19], s[24:25], 2, v[4:5]
	v_lshlrev_b64 v[6:7], 12, v[14:15]
	v_or_b32_e32 v26, 8, v14
	v_or_b32_e32 v30, 16, v14
	v_lshl_add_u64 v[6:7], v[18:19], 0, v[6:7]
	v_ashrrev_i32_e32 v27, 31, v26
	v_ashrrev_i32_e32 v31, 31, v30
	global_load_dwordx4 v[6:9], v[6:7], off sc0 sc1 nt
	v_lshlrev_b64 v[26:27], 12, v[26:27]
	v_lshlrev_b64 v[30:31], 12, v[30:31]
	v_or_b32_e32 v34, 24, v14
	v_lshl_add_u64 v[26:27], v[18:19], 0, v[26:27]
	v_lshl_add_u64 v[30:31], v[18:19], 0, v[30:31]
	v_ashrrev_i32_e32 v35, 31, v34
	v_or_b32_e32 v38, 32, v14
	global_load_dwordx4 v[26:29], v[26:27], off sc0 sc1 nt
	v_lshlrev_b64 v[34:35], 12, v[34:35]
	global_load_dwordx4 v[30:33], v[30:31], off sc0 sc1 nt
	v_ashrrev_i32_e32 v39, 31, v38
	v_lshl_add_u64 v[34:35], v[18:19], 0, v[34:35]
	v_lshlrev_b64 v[38:39], 12, v[38:39]
	v_or_b32_e32 v42, 40, v14
	global_load_dwordx4 v[34:37], v[34:35], off sc0 sc1 nt
	v_lshl_add_u64 v[38:39], v[18:19], 0, v[38:39]
	v_ashrrev_i32_e32 v43, 31, v42
	global_load_dwordx4 v[38:41], v[38:39], off sc0 sc1 nt
	v_lshlrev_b64 v[42:43], 12, v[42:43]
	v_or_b32_e32 v46, 48, v14
	v_lshl_add_u64 v[42:43], v[18:19], 0, v[42:43]
	v_ashrrev_i32_e32 v47, 31, v46
	global_load_dwordx4 v[42:45], v[42:43], off sc0 sc1 nt
	v_lshlrev_b64 v[46:47], 12, v[46:47]
	v_or_b32_e32 v14, 56, v14
	v_lshl_add_u64 v[46:47], v[18:19], 0, v[46:47]
	v_ashrrev_i32_e32 v15, 31, v14
	global_load_dwordx4 v[46:49], v[46:47], off sc0 sc1 nt
	v_lshlrev_b64 v[14:15], 12, v[14:15]
	v_lshl_add_u64 v[14:15], v[18:19], 0, v[14:15]
	global_load_dwordx4 v[50:53], v[14:15], off sc0 sc1 nt
	s_ashr_i32 s19, s18, 31
	s_waitcnt vmcnt(7)
	ds_write2_b32 v22, v6, v7 offset1:1
	ds_write2_b32 v22, v8, v9 offset0:2 offset1:3
	v_add_u32_e32 v6, v21, v23
	v_add_u32_e32 v7, 0x420, v6
	s_waitcnt vmcnt(6)
	ds_write2_b32 v6, v26, v27 offset1:1
	ds_write2_b32 v6, v28, v29 offset0:2 offset1:3
	s_waitcnt vmcnt(5)
	ds_write2_b32 v7, v30, v31 offset1:1
	v_add_u32_e32 v7, 0x428, v6
	ds_write2_b32 v7, v32, v33 offset1:1
	v_add_u32_e32 v7, 0x840, v6
	v_add_u32_e32 v6, 0x848, v6
	s_waitcnt vmcnt(4)
	ds_write2_b32 v6, v36, v37 offset1:1
	v_add_u32_e32 v6, 0x1080, v22
	ds_write2_b32 v7, v34, v35 offset1:1
	s_waitcnt vmcnt(3)
	ds_write2_b32 v6, v38, v39 offset1:1
	v_add_u32_e32 v6, 0x1088, v22
	ds_write2_b32 v6, v40, v41 offset1:1
	v_add_u32_e32 v6, 0x14a0, v22
	v_add_u32_e32 v40, s24, v0
	s_waitcnt vmcnt(2)
	ds_write2_b32 v6, v42, v43 offset1:1
	v_add_u32_e32 v6, 0x14a8, v22
	ds_write2_b32 v6, v44, v45 offset1:1
	v_add_u32_e32 v6, 0x18c0, v22
	v_ashrrev_i32_e32 v41, 31, v40
	s_waitcnt vmcnt(1)
	ds_write2_b32 v6, v46, v47 offset1:1
	v_add_u32_e32 v6, 0x18c8, v22
	ds_write2_b32 v6, v48, v49 offset1:1
	v_add_u32_e32 v6, 0x1ce0, v22
	s_waitcnt vmcnt(0)
	ds_write2_b32 v6, v50, v51 offset1:1
	v_add_u32_e32 v6, 0x1ce8, v22
	ds_write2_b32 v6, v52, v53 offset1:1
	s_waitcnt lgkmcnt(0)
	ds_read2_b32 v[8:9], v24 offset0:33 offset1:41
	ds_read2_b32 v[14:15], v24 offset1:8
	ds_read2_b32 v[18:19], v24 offset0:66 offset1:74
	ds_read2_b32 v[30:31], v24 offset0:99 offset1:107
	ds_read2_b32 v[32:33], v24 offset0:132 offset1:140
	ds_read2_b32 v[34:35], v24 offset0:165 offset1:173
	ds_read2_b32 v[36:37], v24 offset0:198 offset1:206
	ds_read2_b32 v[38:39], v24 offset0:231 offset1:239
	v_lshl_add_u64 v[6:7], s[18:19], 1, v[16:17]
	v_lshlrev_b64 v[42:43], 12, v[40:41]
	s_waitcnt lgkmcnt(6)
	v_cvt_pk_bf16_f32 v26, v14, v8
	s_waitcnt lgkmcnt(4)
	v_cvt_pk_bf16_f32 v27, v18, v30
	s_waitcnt lgkmcnt(2)
	v_cvt_pk_bf16_f32 v28, v32, v34
	s_waitcnt lgkmcnt(0)
	v_cvt_pk_bf16_f32 v29, v36, v38
	v_lshl_add_u64 v[42:43], v[6:7], 0, v[42:43]
	v_add_u32_e32 v8, 8, v40
	global_store_dwordx4 v[42:43], v[26:29], off
	v_add_u32_e32 v42, 16, v40
	v_ashrrev_i32_e32 v43, 31, v42
	v_cvt_pk_bf16_f32 v26, v15, v9
	v_ashrrev_i32_e32 v9, 31, v8
	v_lshlrev_b64 v[8:9], 12, v[8:9]
	v_cvt_pk_bf16_f32 v27, v19, v31
	v_cvt_pk_bf16_f32 v28, v33, v35
	v_cvt_pk_bf16_f32 v29, v37, v39
	v_lshl_add_u64 v[8:9], v[6:7], 0, v[8:9]
	global_store_dwordx4 v[8:9], v[26:29], off
	ds_read2_b32 v[8:9], v24 offset0:49 offset1:57
	ds_read2_b32 v[14:15], v24 offset0:16 offset1:24
	ds_read2_b32 v[18:19], v24 offset0:82 offset1:90
	ds_read2_b32 v[30:31], v24 offset0:115 offset1:123
	ds_read2_b32 v[32:33], v24 offset0:148 offset1:156
	ds_read2_b32 v[34:35], v24 offset0:181 offset1:189
	ds_read2_b32 v[36:37], v24 offset0:214 offset1:222
	ds_read2_b32 v[38:39], v24 offset0:247 offset1:255
	v_lshlrev_b64 v[42:43], 12, v[42:43]
	s_waitcnt lgkmcnt(6)
	v_cvt_pk_bf16_f32 v26, v14, v8
	s_waitcnt lgkmcnt(4)
	v_cvt_pk_bf16_f32 v27, v18, v30
	s_waitcnt lgkmcnt(2)
	v_cvt_pk_bf16_f32 v28, v32, v34
	s_waitcnt lgkmcnt(0)
	v_cvt_pk_bf16_f32 v29, v36, v38
	v_lshl_add_u64 v[42:43], v[6:7], 0, v[42:43]
	v_add_u32_e32 v8, 24, v40
	global_store_dwordx4 v[42:43], v[26:29], off
	s_nop 1
	v_cvt_pk_bf16_f32 v26, v15, v9
	v_ashrrev_i32_e32 v9, 31, v8
	v_lshlrev_b64 v[8:9], 12, v[8:9]
	v_cvt_pk_bf16_f32 v27, v19, v31
	v_cvt_pk_bf16_f32 v28, v33, v35
	v_cvt_pk_bf16_f32 v29, v37, v39
	v_lshl_add_u64 v[6:7], v[6:7], 0, v[8:9]
	global_store_dwordx4 v[6:7], v[26:29], off
	s_waitcnt lgkmcnt(0)
	s_cbranch_execnz .LBB0_1049
	s_branch .LBB0_1048

.LBB0_1059:
	s_lshr_b32 s13, s11, 31
	s_add_i32 s13, s11, s13
	s_lshl_b32 s13, s13, 5
	s_and_b32 s36, s13, 0xffffffc0
	s_andn2_b64 vcc, exec, s[18:19]
	s_sub_i32 s13, 0, s36
	s_cbranch_vccnz .LBB0_1061
	s_add_i32 s38, s12, s13
	v_or_b32_e32 v8, s36, v20
	s_ashr_i32 s39, s38, 31
	v_ashrrev_i32_e32 v9, 31, v8
	v_or_b32_e32 v34, 8, v8
	v_or_b32_e32 v38, 16, v8
	v_lshl_add_u64 v[18:19], s[38:39], 2, v[2:3]
	v_lshlrev_b64 v[4:5], 8, v[8:9]
	v_ashrrev_i32_e32 v35, 31, v34
	v_ashrrev_i32_e32 v39, 31, v38
	v_lshl_add_u64 v[4:5], v[18:19], 0, v[4:5]
	v_lshlrev_b64 v[34:35], 8, v[34:35]
	v_lshlrev_b64 v[38:39], 8, v[38:39]
	v_or_b32_e32 v42, 24, v8
	global_load_dwordx4 v[4:7], v[4:5], off sc0 sc1 nt
	v_lshl_add_u64 v[34:35], v[18:19], 0, v[34:35]
	v_lshl_add_u64 v[38:39], v[18:19], 0, v[38:39]
	v_ashrrev_i32_e32 v43, 31, v42
	v_or_b32_e32 v46, 32, v8
	global_load_dwordx4 v[34:37], v[34:35], off sc0 sc1 nt
	v_lshlrev_b64 v[42:43], 8, v[42:43]
	global_load_dwordx4 v[38:41], v[38:39], off sc0 sc1 nt
	v_ashrrev_i32_e32 v47, 31, v46
	v_lshl_add_u64 v[42:43], v[18:19], 0, v[42:43]
	v_lshlrev_b64 v[46:47], 8, v[46:47]
	v_or_b32_e32 v50, 40, v8
	global_load_dwordx4 v[42:45], v[42:43], off sc0 sc1 nt
	v_lshl_add_u64 v[46:47], v[18:19], 0, v[46:47]
	v_ashrrev_i32_e32 v51, 31, v50
	global_load_dwordx4 v[46:49], v[46:47], off sc0 sc1 nt
	v_lshlrev_b64 v[50:51], 8, v[50:51]
	v_or_b32_e32 v54, 48, v8
	v_lshl_add_u64 v[50:51], v[18:19], 0, v[50:51]
	v_ashrrev_i32_e32 v55, 31, v54
	global_load_dwordx4 v[50:53], v[50:51], off sc0 sc1 nt
	v_lshlrev_b64 v[54:55], 8, v[54:55]
	v_or_b32_e32 v8, 56, v8
	v_lshl_add_u64 v[54:55], v[18:19], 0, v[54:55]
	v_ashrrev_i32_e32 v9, 31, v8
	global_load_dwordx4 v[54:57], v[54:55], off sc0 sc1 nt
	v_lshlrev_b64 v[8:9], 8, v[8:9]
	v_lshl_add_u64 v[8:9], v[18:19], 0, v[8:9]
	global_load_dwordx4 v[58:61], v[8:9], off sc0 sc1 nt
	v_add_u32_e32 v0, v21, v23
	v_add_u32_e32 v11, s38, v13
	s_ashr_i32 s37, s36, 31
	s_waitcnt vmcnt(7)
	ds_write2_b32 v22, v4, v5 offset1:1
	ds_write2_b32 v22, v6, v7 offset0:2 offset1:3
	v_add_u32_e32 v4, 0x420, v0
	s_waitcnt vmcnt(6)
	ds_write2_b32 v0, v34, v35 offset1:1
	ds_write2_b32 v0, v36, v37 offset0:2 offset1:3
	s_waitcnt vmcnt(5)
	ds_write2_b32 v4, v38, v39 offset1:1
	v_add_u32_e32 v4, 0x428, v0
	ds_write2_b32 v4, v40, v41 offset1:1
	v_add_u32_e32 v4, 0x840, v0
	v_add_u32_e32 v0, 0x848, v0
	s_waitcnt vmcnt(4)
	ds_write2_b32 v0, v44, v45 offset1:1
	v_add_u32_e32 v0, 0x1080, v22
	ds_write2_b32 v4, v42, v43 offset1:1
	s_waitcnt vmcnt(3)
	ds_write2_b32 v0, v46, v47 offset1:1
	v_add_u32_e32 v0, 0x1088, v22
	ds_write2_b32 v0, v48, v49 offset1:1
	v_add_u32_e32 v0, 0x14a0, v22
	v_lshl_add_u64 v[4:5], s[36:37], 1, v[16:17]
	s_waitcnt vmcnt(2)
	ds_write2_b32 v0, v50, v51 offset1:1
	v_add_u32_e32 v0, 0x14a8, v22
	ds_write2_b32 v0, v52, v53 offset1:1
	v_add_u32_e32 v0, 0x18c0, v22
	s_waitcnt vmcnt(1)
	ds_write2_b32 v0, v54, v55 offset1:1
	v_add_u32_e32 v0, 0x18c8, v22
	ds_write2_b32 v0, v56, v57 offset1:1
	v_add_u32_e32 v0, 0x1ce0, v22
	s_waitcnt vmcnt(0)
	ds_write2_b32 v0, v58, v59 offset1:1
	v_add_u32_e32 v0, 0x1ce8, v22
	ds_write2_b32 v0, v60, v61 offset1:1
	s_waitcnt lgkmcnt(0)
	ds_read2_b32 v[18:19], v24 offset0:33 offset1:41
	ds_read2_b32 v[34:35], v24 offset1:8
	ds_read2_b32 v[36:37], v24 offset0:66 offset1:74
	ds_read2_b32 v[38:39], v24 offset0:99 offset1:107
	ds_read2_b32 v[40:41], v24 offset0:132 offset1:140
	ds_read2_b32 v[42:43], v24 offset0:165 offset1:173
	ds_read2_b32 v[44:45], v24 offset0:198 offset1:206
	ds_read2_b32 v[46:47], v24 offset0:231 offset1:239
	v_add_u32_e32 v0, 0xc00, v11
	v_lshlrev_b64 v[48:49], 12, v[0:1]
	s_waitcnt lgkmcnt(6)
	v_cvt_pk_bf16_f32 v6, v34, v18
	s_waitcnt lgkmcnt(4)
	v_cvt_pk_bf16_f32 v7, v36, v38
	s_waitcnt lgkmcnt(2)
	v_cvt_pk_bf16_f32 v8, v40, v42
	s_waitcnt lgkmcnt(0)
	v_cvt_pk_bf16_f32 v9, v44, v46
	v_lshl_add_u64 v[48:49], v[4:5], 0, v[48:49]
	v_add_u32_e32 v0, 0xc08, v11
	global_store_dwordx4 v[48:49], v[6:9], off
	s_nop 1
	v_cvt_pk_bf16_f32 v6, v35, v19
	v_lshlrev_b64 v[18:19], 12, v[0:1]
	v_cvt_pk_bf16_f32 v7, v37, v39
	v_cvt_pk_bf16_f32 v8, v41, v43
	v_cvt_pk_bf16_f32 v9, v45, v47
	v_lshl_add_u64 v[18:19], v[4:5], 0, v[18:19]
	global_store_dwordx4 v[18:19], v[6:9], off
	ds_read2_b32 v[18:19], v24 offset0:49 offset1:57
	ds_read2_b32 v[34:35], v24 offset0:16 offset1:24
	ds_read2_b32 v[36:37], v24 offset0:82 offset1:90
	ds_read2_b32 v[38:39], v24 offset0:115 offset1:123
	ds_read2_b32 v[40:41], v24 offset0:148 offset1:156
	ds_read2_b32 v[42:43], v24 offset0:181 offset1:189
	ds_read2_b32 v[44:45], v24 offset0:214 offset1:222
	ds_read2_b32 v[46:47], v24 offset0:247 offset1:255
	v_add_u32_e32 v0, 0xc10, v11
	v_lshlrev_b64 v[48:49], 12, v[0:1]
	s_waitcnt lgkmcnt(6)
	v_cvt_pk_bf16_f32 v6, v34, v18
	s_waitcnt lgkmcnt(4)
	v_cvt_pk_bf16_f32 v7, v36, v38
	s_waitcnt lgkmcnt(2)
	v_cvt_pk_bf16_f32 v8, v40, v42
	s_waitcnt lgkmcnt(0)
	v_cvt_pk_bf16_f32 v9, v44, v46
	v_lshl_add_u64 v[48:49], v[4:5], 0, v[48:49]
	v_add_u32_e32 v0, 0xc18, v11
	global_store_dwordx4 v[48:49], v[6:9], off
	s_nop 1
	v_cvt_pk_bf16_f32 v6, v35, v19
	v_lshlrev_b64 v[18:19], 12, v[0:1]
	v_cvt_pk_bf16_f32 v7, v37, v39
	v_cvt_pk_bf16_f32 v8, v41, v43
	v_cvt_pk_bf16_f32 v9, v45, v47
	v_lshl_add_u64 v[4:5], v[4:5], 0, v[18:19]
	global_store_dwordx4 v[4:5], v[6:9], off
	s_waitcnt lgkmcnt(0)
	s_cbranch_execnz .LBB0_1058
	s_branch .LBB0_1057

.LBB0_1066:
	s_lshr_b32 s13, s11, 31
	s_add_i32 s13, s11, s13
	s_lshl_b32 s13, s13, 5
	s_and_b32 s34, s13, 0xffffffc0
	s_andn2_b64 vcc, exec, s[18:19]
	s_sub_i32 s13, 0, s34
	s_cbranch_vccnz .LBB0_1068
	s_add_i32 s36, s12, s13
	v_or_b32_e32 v58, s34, v20
	s_ashr_i32 s37, s36, 31
	v_ashrrev_i32_e32 v59, 31, v58
	v_lshl_add_u64 v[2:3], s[36:37], 2, v[18:19]
	v_lshlrev_b64 v[4:5], 8, v[58:59]
	v_lshl_add_u64 v[4:5], v[2:3], 0, v[4:5]
	global_load_dwordx4 v[34:37], v[4:5], off sc0 sc1 nt
	v_or_b32_e32 v4, 8, v58
	v_ashrrev_i32_e32 v5, 31, v4
	v_lshlrev_b64 v[4:5], 8, v[4:5]
	v_lshl_add_u64 v[4:5], v[2:3], 0, v[4:5]
	global_load_dwordx4 v[38:41], v[4:5], off sc0 sc1 nt
	v_or_b32_e32 v4, 16, v58
	v_ashrrev_i32_e32 v5, 31, v4
	v_lshlrev_b64 v[4:5], 8, v[4:5]
	v_lshl_add_u64 v[4:5], v[2:3], 0, v[4:5]
	global_load_dwordx4 v[42:45], v[4:5], off sc0 sc1 nt
	v_or_b32_e32 v4, 24, v58
	v_ashrrev_i32_e32 v5, 31, v4
	v_lshlrev_b64 v[4:5], 8, v[4:5]
	v_lshl_add_u64 v[4:5], v[2:3], 0, v[4:5]
	global_load_dwordx4 v[46:49], v[4:5], off sc0 sc1 nt
	v_or_b32_e32 v4, 32, v58
	v_ashrrev_i32_e32 v5, 31, v4
	v_lshlrev_b64 v[4:5], 8, v[4:5]
	v_lshl_add_u64 v[4:5], v[2:3], 0, v[4:5]
	global_load_dwordx4 v[50:53], v[4:5], off sc0 sc1 nt
	v_or_b32_e32 v4, 40, v58
	v_ashrrev_i32_e32 v5, 31, v4
	v_lshlrev_b64 v[4:5], 8, v[4:5]
	v_lshl_add_u64 v[4:5], v[2:3], 0, v[4:5]
	global_load_dwordx4 v[54:57], v[4:5], off sc0 sc1 nt
	v_or_b32_e32 v4, 48, v58
	v_ashrrev_i32_e32 v5, 31, v4
	v_lshlrev_b64 v[4:5], 8, v[4:5]
	v_lshl_add_u64 v[4:5], v[2:3], 0, v[4:5]
	global_load_dwordx4 v[6:9], v[4:5], off sc0 sc1 nt
	v_or_b32_e32 v4, 56, v58
	v_lshl_add_u64 v[58:59], v[58:59], 2, s[24:25]
	global_load_dword v0, v[58:59], off
	v_ashrrev_i32_e32 v5, 31, v4
	v_lshlrev_b64 v[4:5], 8, v[4:5]
	v_lshl_add_u64 v[2:3], v[2:3], 0, v[4:5]
	global_load_dwordx4 v[2:5], v[2:3], off sc0 sc1 nt
	v_add_u32_e32 v11, v21, v23
	s_ashr_i32 s35, s34, 31
	s_waitcnt vmcnt(1)
	v_pk_mul_f32 v[34:35], v[34:35], v[0:1] op_sel_hi:[1,0]
	v_pk_mul_f32 v[36:37], v[36:37], v[0:1] op_sel_hi:[1,0]
	ds_write2_b32 v22, v34, v35 offset1:1
	ds_write2_b32 v22, v36, v37 offset0:2 offset1:3
	v_or_b32_e32 v34, s34, v26
	v_ashrrev_i32_e32 v35, 31, v34
	v_lshl_add_u64 v[34:35], v[34:35], 2, s[24:25]
	global_load_dword v0, v[34:35], off
	s_waitcnt vmcnt(0)
	v_pk_mul_f32 v[34:35], v[40:41], v[0:1] op_sel_hi:[1,0]
	v_pk_mul_f32 v[36:37], v[38:39], v[0:1] op_sel_hi:[1,0]
	ds_write2_b32 v11, v36, v37 offset1:1
	ds_write2_b32 v11, v34, v35 offset0:2 offset1:3
	v_or_b32_e32 v34, s34, v27
	v_ashrrev_i32_e32 v35, 31, v34
	v_lshl_add_u64 v[34:35], v[34:35], 2, s[24:25]
	global_load_dword v0, v[34:35], off
	s_waitcnt vmcnt(0)
	v_pk_mul_f32 v[34:35], v[44:45], v[0:1] op_sel_hi:[1,0]
	v_pk_mul_f32 v[36:37], v[42:43], v[0:1] op_sel_hi:[1,0]
	v_add_u32_e32 v0, 0x420, v11
	ds_write2_b32 v0, v36, v37 offset1:1
	v_add_u32_e32 v0, 0x428, v11
	ds_write2_b32 v0, v34, v35 offset1:1
	v_or_b32_e32 v34, s34, v25
	v_ashrrev_i32_e32 v35, 31, v34
	v_lshl_add_u64 v[34:35], v[34:35], 2, s[24:25]
	global_load_dword v0, v[34:35], off
	s_waitcnt vmcnt(0)
	v_pk_mul_f32 v[34:35], v[48:49], v[0:1] op_sel_hi:[1,0]
	v_pk_mul_f32 v[36:37], v[46:47], v[0:1] op_sel_hi:[1,0]
	v_add_u32_e32 v0, 0x840, v11
	ds_write2_b32 v0, v36, v37 offset1:1
	v_add_u32_e32 v0, 0x848, v11
	ds_write2_b32 v0, v34, v35 offset1:1
	v_or_b32_e32 v34, s34, v28
	v_ashrrev_i32_e32 v35, 31, v34
	v_lshl_add_u64 v[34:35], v[34:35], 2, s[24:25]
	global_load_dword v0, v[34:35], off
	v_add_u32_e32 v11, v21, v29
	s_waitcnt vmcnt(0)
	v_pk_mul_f32 v[34:35], v[52:53], v[0:1] op_sel_hi:[1,0]
	v_pk_mul_f32 v[36:37], v[50:51], v[0:1] op_sel_hi:[1,0]
	ds_write2_b32 v11, v36, v37 offset1:1
	ds_write2_b32 v11, v34, v35 offset0:2 offset1:3
	v_or_b32_e32 v34, s34, v30
	v_ashrrev_i32_e32 v35, 31, v34
	v_lshl_add_u64 v[34:35], v[34:35], 2, s[24:25]
	global_load_dword v0, v[34:35], off
	s_waitcnt vmcnt(0)
	v_pk_mul_f32 v[34:35], v[56:57], v[0:1] op_sel_hi:[1,0]
	v_pk_mul_f32 v[36:37], v[54:55], v[0:1] op_sel_hi:[1,0]
	v_add_u32_e32 v0, 0x420, v11
	ds_write2_b32 v0, v36, v37 offset1:1
	v_add_u32_e32 v0, 0x428, v11
	ds_write2_b32 v0, v34, v35 offset1:1
	v_or_b32_e32 v34, s34, v31
	v_ashrrev_i32_e32 v35, 31, v34
	v_lshl_add_u64 v[34:35], v[34:35], 2, s[24:25]
	global_load_dword v0, v[34:35], off
	s_waitcnt vmcnt(0)
	v_pk_mul_f32 v[8:9], v[8:9], v[0:1] op_sel_hi:[1,0]
	v_pk_mul_f32 v[6:7], v[6:7], v[0:1] op_sel_hi:[1,0]
	v_add_u32_e32 v0, 0x840, v11
	ds_write2_b32 v0, v6, v7 offset1:1
	v_or_b32_e32 v6, s34, v32
	v_ashrrev_i32_e32 v7, 31, v6
	v_add_u32_e32 v0, 0x848, v11
	v_lshl_add_u64 v[6:7], v[6:7], 2, s[24:25]
	ds_write2_b32 v0, v8, v9 offset1:1
	global_load_dword v0, v[6:7], off
	v_lshl_add_u64 v[6:7], s[34:35], 1, v[14:15]
	s_waitcnt vmcnt(0)
	v_pk_mul_f32 v[4:5], v[4:5], v[0:1] op_sel_hi:[1,0]
	v_pk_mul_f32 v[2:3], v[2:3], v[0:1] op_sel_hi:[1,0]
	v_add_u32_e32 v0, 0xc60, v11
	ds_write2_b32 v0, v2, v3 offset1:1
	v_add_u32_e32 v0, 0xc68, v11
	ds_write2_b32 v0, v4, v5 offset1:1
	s_waitcnt lgkmcnt(0)
	ds_read2_b32 v[8:9], v24 offset0:33 offset1:41
	ds_read2_b32 v[34:35], v24 offset1:8
	ds_read2_b32 v[36:37], v24 offset0:66 offset1:74
	ds_read2_b32 v[38:39], v24 offset0:99 offset1:107
	ds_read2_b32 v[40:41], v24 offset0:132 offset1:140
	ds_read2_b32 v[42:43], v24 offset0:165 offset1:173
	ds_read2_b32 v[44:45], v24 offset0:198 offset1:206
	ds_read2_b32 v[46:47], v24 offset0:231 offset1:239
	v_add_u32_e32 v11, s36, v13
	v_add_u32_e32 v0, 0xc00, v11
	v_lshlrev_b64 v[48:49], 12, v[0:1]
	s_waitcnt lgkmcnt(6)
	v_cvt_pk_bf16_f32 v2, v34, v8
	s_waitcnt lgkmcnt(4)
	v_cvt_pk_bf16_f32 v3, v36, v38
	s_waitcnt lgkmcnt(2)
	v_cvt_pk_bf16_f32 v4, v40, v42
	s_waitcnt lgkmcnt(0)
	v_cvt_pk_bf16_f32 v5, v44, v46
	v_lshl_add_u64 v[48:49], v[6:7], 0, v[48:49]
	v_add_u32_e32 v0, 0xc08, v11
	global_store_dwordx4 v[48:49], v[2:5], off
	s_nop 1
	v_cvt_pk_bf16_f32 v2, v35, v9
	v_lshlrev_b64 v[8:9], 12, v[0:1]
	v_cvt_pk_bf16_f32 v3, v37, v39
	v_cvt_pk_bf16_f32 v4, v41, v43
	v_cvt_pk_bf16_f32 v5, v45, v47
	v_lshl_add_u64 v[8:9], v[6:7], 0, v[8:9]
	global_store_dwordx4 v[8:9], v[2:5], off
	ds_read2_b32 v[8:9], v24 offset0:49 offset1:57
	ds_read2_b32 v[34:35], v24 offset0:16 offset1:24
	ds_read2_b32 v[36:37], v24 offset0:82 offset1:90
	ds_read2_b32 v[38:39], v24 offset0:115 offset1:123
	ds_read2_b32 v[40:41], v24 offset0:148 offset1:156
	ds_read2_b32 v[42:43], v24 offset0:181 offset1:189
	ds_read2_b32 v[44:45], v24 offset0:214 offset1:222
	ds_read2_b32 v[46:47], v24 offset0:247 offset1:255
	v_add_u32_e32 v0, 0xc10, v11
	v_lshlrev_b64 v[48:49], 12, v[0:1]
	s_waitcnt lgkmcnt(6)
	v_cvt_pk_bf16_f32 v2, v34, v8
	s_waitcnt lgkmcnt(4)
	v_cvt_pk_bf16_f32 v3, v36, v38
	s_waitcnt lgkmcnt(2)
	v_cvt_pk_bf16_f32 v4, v40, v42
	s_waitcnt lgkmcnt(0)
	v_cvt_pk_bf16_f32 v5, v44, v46
	v_lshl_add_u64 v[48:49], v[6:7], 0, v[48:49]
	v_add_u32_e32 v0, 0xc18, v11
	global_store_dwordx4 v[48:49], v[2:5], off
	s_nop 1
	v_cvt_pk_bf16_f32 v2, v35, v9
	v_lshlrev_b64 v[8:9], 12, v[0:1]
	v_cvt_pk_bf16_f32 v3, v37, v39
	v_cvt_pk_bf16_f32 v4, v41, v43
	v_cvt_pk_bf16_f32 v5, v45, v47
	v_lshl_add_u64 v[6:7], v[6:7], 0, v[8:9]
	global_store_dwordx4 v[6:7], v[2:5], off
	s_waitcnt lgkmcnt(0)
	s_cbranch_execnz .LBB0_1065
	s_branch .LBB0_1064

.LBB0_1073:
	s_lshr_b32 s13, s11, 31
	s_add_i32 s13, s11, s13
	s_lshl_b32 s13, s13, 5
	s_and_b32 s38, s13, 0xffffffc0
	s_andn2_b64 vcc, exec, s[30:31]
	s_sub_i32 s13, 0, s38
	s_cbranch_vccnz .LBB0_1075
	s_add_i32 s42, s12, s13
	v_or_b32_e32 v8, s38, v20
	s_ashr_i32 s43, s42, 31
	v_ashrrev_i32_e32 v9, 31, v8
	v_or_b32_e32 v34, 8, v8
	v_or_b32_e32 v38, 16, v8
	v_lshl_add_u64 v[18:19], s[42:43], 2, v[2:3]
	v_lshlrev_b64 v[4:5], 8, v[8:9]
	v_ashrrev_i32_e32 v35, 31, v34
	v_ashrrev_i32_e32 v39, 31, v38
	v_lshl_add_u64 v[4:5], v[18:19], 0, v[4:5]
	v_lshlrev_b64 v[34:35], 8, v[34:35]
	v_lshlrev_b64 v[38:39], 8, v[38:39]
	v_or_b32_e32 v42, 24, v8
	global_load_dwordx4 v[4:7], v[4:5], off sc0 sc1 nt
	v_lshl_add_u64 v[34:35], v[18:19], 0, v[34:35]
	v_lshl_add_u64 v[38:39], v[18:19], 0, v[38:39]
	v_ashrrev_i32_e32 v43, 31, v42
	v_or_b32_e32 v46, 32, v8
	global_load_dwordx4 v[34:37], v[34:35], off sc0 sc1 nt
	v_lshlrev_b64 v[42:43], 8, v[42:43]
	global_load_dwordx4 v[38:41], v[38:39], off sc0 sc1 nt
	v_ashrrev_i32_e32 v47, 31, v46
	v_lshl_add_u64 v[42:43], v[18:19], 0, v[42:43]
	v_lshlrev_b64 v[46:47], 8, v[46:47]
	v_or_b32_e32 v50, 40, v8
	global_load_dwordx4 v[42:45], v[42:43], off sc0 sc1 nt
	v_lshl_add_u64 v[46:47], v[18:19], 0, v[46:47]
	v_ashrrev_i32_e32 v51, 31, v50
	global_load_dwordx4 v[46:49], v[46:47], off sc0 sc1 nt
	v_lshlrev_b64 v[50:51], 8, v[50:51]
	v_or_b32_e32 v54, 48, v8
	v_lshl_add_u64 v[50:51], v[18:19], 0, v[50:51]
	v_ashrrev_i32_e32 v55, 31, v54
	global_load_dwordx4 v[50:53], v[50:51], off sc0 sc1 nt
	v_lshlrev_b64 v[54:55], 8, v[54:55]
	v_or_b32_e32 v8, 56, v8
	v_lshl_add_u64 v[54:55], v[18:19], 0, v[54:55]
	v_ashrrev_i32_e32 v9, 31, v8
	global_load_dwordx4 v[54:57], v[54:55], off sc0 sc1 nt
	v_lshlrev_b64 v[8:9], 8, v[8:9]
	v_lshl_add_u64 v[8:9], v[18:19], 0, v[8:9]
	global_load_dwordx4 v[58:61], v[8:9], off sc0 sc1 nt
	v_add_u32_e32 v0, v21, v23
	v_add_u32_e32 v11, s42, v13
	s_ashr_i32 s39, s38, 31
	s_waitcnt vmcnt(7)
	ds_write2_b32 v22, v4, v5 offset1:1
	ds_write2_b32 v22, v6, v7 offset0:2 offset1:3
	v_add_u32_e32 v4, 0x420, v0
	s_waitcnt vmcnt(6)
	ds_write2_b32 v0, v34, v35 offset1:1
	ds_write2_b32 v0, v36, v37 offset0:2 offset1:3
	s_waitcnt vmcnt(5)
	ds_write2_b32 v4, v38, v39 offset1:1
	v_add_u32_e32 v4, 0x428, v0
	ds_write2_b32 v4, v40, v41 offset1:1
	v_add_u32_e32 v4, 0x840, v0
	v_add_u32_e32 v0, 0x848, v0
	s_waitcnt vmcnt(4)
	ds_write2_b32 v0, v44, v45 offset1:1
	v_add_u32_e32 v0, 0x1080, v22
	ds_write2_b32 v4, v42, v43 offset1:1
	s_waitcnt vmcnt(3)
	ds_write2_b32 v0, v46, v47 offset1:1
	v_add_u32_e32 v0, 0x1088, v22
	ds_write2_b32 v0, v48, v49 offset1:1
	v_add_u32_e32 v0, 0x14a0, v22
	v_lshl_add_u64 v[4:5], s[38:39], 1, v[16:17]
	s_waitcnt vmcnt(2)
	ds_write2_b32 v0, v50, v51 offset1:1
	v_add_u32_e32 v0, 0x14a8, v22
	ds_write2_b32 v0, v52, v53 offset1:1
	v_add_u32_e32 v0, 0x18c0, v22
	s_waitcnt vmcnt(1)
	ds_write2_b32 v0, v54, v55 offset1:1
	v_add_u32_e32 v0, 0x18c8, v22
	ds_write2_b32 v0, v56, v57 offset1:1
	v_add_u32_e32 v0, 0x1ce0, v22
	s_waitcnt vmcnt(0)
	ds_write2_b32 v0, v58, v59 offset1:1
	v_add_u32_e32 v0, 0x1ce8, v22
	ds_write2_b32 v0, v60, v61 offset1:1
	s_waitcnt lgkmcnt(0)
	ds_read2_b32 v[18:19], v24 offset0:33 offset1:41
	ds_read2_b32 v[34:35], v24 offset1:8
	ds_read2_b32 v[36:37], v24 offset0:66 offset1:74
	ds_read2_b32 v[38:39], v24 offset0:99 offset1:107
	ds_read2_b32 v[40:41], v24 offset0:132 offset1:140
	ds_read2_b32 v[42:43], v24 offset0:165 offset1:173
	ds_read2_b32 v[44:45], v24 offset0:198 offset1:206
	ds_read2_b32 v[46:47], v24 offset0:231 offset1:239
	v_add_u32_e32 v0, 0xc80, v11
	v_lshlrev_b64 v[48:49], 12, v[0:1]
	s_waitcnt lgkmcnt(6)
	v_cvt_pk_bf16_f32 v6, v34, v18
	s_waitcnt lgkmcnt(4)
	v_cvt_pk_bf16_f32 v7, v36, v38
	s_waitcnt lgkmcnt(2)
	v_cvt_pk_bf16_f32 v8, v40, v42
	s_waitcnt lgkmcnt(0)
	v_cvt_pk_bf16_f32 v9, v44, v46
	v_lshl_add_u64 v[48:49], v[4:5], 0, v[48:49]
	v_add_u32_e32 v0, 0xc88, v11
	global_store_dwordx4 v[48:49], v[6:9], off
	s_nop 1
	v_cvt_pk_bf16_f32 v6, v35, v19
	v_lshlrev_b64 v[18:19], 12, v[0:1]
	v_cvt_pk_bf16_f32 v7, v37, v39
	v_cvt_pk_bf16_f32 v8, v41, v43
	v_cvt_pk_bf16_f32 v9, v45, v47
	v_lshl_add_u64 v[18:19], v[4:5], 0, v[18:19]
	global_store_dwordx4 v[18:19], v[6:9], off
	ds_read2_b32 v[18:19], v24 offset0:49 offset1:57
	ds_read2_b32 v[34:35], v24 offset0:16 offset1:24
	ds_read2_b32 v[36:37], v24 offset0:82 offset1:90
	ds_read2_b32 v[38:39], v24 offset0:115 offset1:123
	ds_read2_b32 v[40:41], v24 offset0:148 offset1:156
	ds_read2_b32 v[42:43], v24 offset0:181 offset1:189
	ds_read2_b32 v[44:45], v24 offset0:214 offset1:222
	ds_read2_b32 v[46:47], v24 offset0:247 offset1:255
	v_add_u32_e32 v0, 0xc90, v11
	v_lshlrev_b64 v[48:49], 12, v[0:1]
	s_waitcnt lgkmcnt(6)
	v_cvt_pk_bf16_f32 v6, v34, v18
	s_waitcnt lgkmcnt(4)
	v_cvt_pk_bf16_f32 v7, v36, v38
	s_waitcnt lgkmcnt(2)
	v_cvt_pk_bf16_f32 v8, v40, v42
	s_waitcnt lgkmcnt(0)
	v_cvt_pk_bf16_f32 v9, v44, v46
	v_lshl_add_u64 v[48:49], v[4:5], 0, v[48:49]
	v_add_u32_e32 v0, 0xc98, v11
	global_store_dwordx4 v[48:49], v[6:9], off
	s_nop 1
	v_cvt_pk_bf16_f32 v6, v35, v19
	v_lshlrev_b64 v[18:19], 12, v[0:1]
	v_cvt_pk_bf16_f32 v7, v37, v39
	v_cvt_pk_bf16_f32 v8, v41, v43
	v_cvt_pk_bf16_f32 v9, v45, v47
	v_lshl_add_u64 v[4:5], v[4:5], 0, v[18:19]
	global_store_dwordx4 v[4:5], v[6:9], off
	s_waitcnt lgkmcnt(0)
	s_cbranch_execnz .LBB0_1072
	s_branch .LBB0_1071

.LBB0_1080:
	s_lshr_b32 s12, s10, 31
	s_add_i32 s12, s10, s12
	s_lshl_b32 s12, s12, 5
	s_and_b32 s34, s12, 0xffffffc0
	s_andn2_b64 vcc, exec, s[30:31]
	s_sub_i32 s12, 0, s34
	s_cbranch_vccnz .LBB0_1082
	s_add_i32 s36, s11, s12
	v_or_b32_e32 v58, s34, v20
	s_ashr_i32 s37, s36, 31
	v_ashrrev_i32_e32 v59, 31, v58
	v_lshl_add_u64 v[2:3], s[36:37], 2, v[18:19]
	v_lshlrev_b64 v[4:5], 8, v[58:59]
	v_lshl_add_u64 v[4:5], v[2:3], 0, v[4:5]
	global_load_dwordx4 v[34:37], v[4:5], off sc0 sc1 nt
	v_or_b32_e32 v4, 8, v58
	v_ashrrev_i32_e32 v5, 31, v4
	v_lshlrev_b64 v[4:5], 8, v[4:5]
	v_lshl_add_u64 v[4:5], v[2:3], 0, v[4:5]
	global_load_dwordx4 v[38:41], v[4:5], off sc0 sc1 nt
	v_or_b32_e32 v4, 16, v58
	v_ashrrev_i32_e32 v5, 31, v4
	v_lshlrev_b64 v[4:5], 8, v[4:5]
	v_lshl_add_u64 v[4:5], v[2:3], 0, v[4:5]
	global_load_dwordx4 v[42:45], v[4:5], off sc0 sc1 nt
	v_or_b32_e32 v4, 24, v58
	v_ashrrev_i32_e32 v5, 31, v4
	v_lshlrev_b64 v[4:5], 8, v[4:5]
	v_lshl_add_u64 v[4:5], v[2:3], 0, v[4:5]
	global_load_dwordx4 v[46:49], v[4:5], off sc0 sc1 nt
	v_or_b32_e32 v4, 32, v58
	v_ashrrev_i32_e32 v5, 31, v4
	v_lshlrev_b64 v[4:5], 8, v[4:5]
	v_lshl_add_u64 v[4:5], v[2:3], 0, v[4:5]
	global_load_dwordx4 v[50:53], v[4:5], off sc0 sc1 nt
	v_or_b32_e32 v4, 40, v58
	v_ashrrev_i32_e32 v5, 31, v4
	v_lshlrev_b64 v[4:5], 8, v[4:5]
	v_lshl_add_u64 v[4:5], v[2:3], 0, v[4:5]
	global_load_dwordx4 v[54:57], v[4:5], off sc0 sc1 nt
	v_or_b32_e32 v4, 48, v58
	v_ashrrev_i32_e32 v5, 31, v4
	v_lshlrev_b64 v[4:5], 8, v[4:5]
	v_lshl_add_u64 v[4:5], v[2:3], 0, v[4:5]
	global_load_dwordx4 v[6:9], v[4:5], off sc0 sc1 nt
	v_or_b32_e32 v4, 56, v58
	v_lshl_add_u64 v[58:59], v[58:59], 2, s[26:27]
	global_load_dword v0, v[58:59], off
	v_ashrrev_i32_e32 v5, 31, v4
	v_lshlrev_b64 v[4:5], 8, v[4:5]
	v_lshl_add_u64 v[2:3], v[2:3], 0, v[4:5]
	global_load_dwordx4 v[2:5], v[2:3], off sc0 sc1 nt
	v_add_u32_e32 v11, v21, v23
	s_ashr_i32 s35, s34, 31
	s_waitcnt vmcnt(1)
	v_pk_mul_f32 v[34:35], v[34:35], v[0:1] op_sel_hi:[1,0]
	v_pk_mul_f32 v[36:37], v[36:37], v[0:1] op_sel_hi:[1,0]
	ds_write2_b32 v22, v34, v35 offset1:1
	ds_write2_b32 v22, v36, v37 offset0:2 offset1:3
	v_or_b32_e32 v34, s34, v26
	v_ashrrev_i32_e32 v35, 31, v34
	v_lshl_add_u64 v[34:35], v[34:35], 2, s[26:27]
	global_load_dword v0, v[34:35], off
	s_waitcnt vmcnt(0)
	v_pk_mul_f32 v[34:35], v[40:41], v[0:1] op_sel_hi:[1,0]
	v_pk_mul_f32 v[36:37], v[38:39], v[0:1] op_sel_hi:[1,0]
	ds_write2_b32 v11, v36, v37 offset1:1
	ds_write2_b32 v11, v34, v35 offset0:2 offset1:3
	v_or_b32_e32 v34, s34, v27
	v_ashrrev_i32_e32 v35, 31, v34
	v_lshl_add_u64 v[34:35], v[34:35], 2, s[26:27]
	global_load_dword v0, v[34:35], off
	s_waitcnt vmcnt(0)
	v_pk_mul_f32 v[34:35], v[44:45], v[0:1] op_sel_hi:[1,0]
	v_pk_mul_f32 v[36:37], v[42:43], v[0:1] op_sel_hi:[1,0]
	v_add_u32_e32 v0, 0x420, v11
	ds_write2_b32 v0, v36, v37 offset1:1
	v_add_u32_e32 v0, 0x428, v11
	ds_write2_b32 v0, v34, v35 offset1:1
	v_or_b32_e32 v34, s34, v25
	v_ashrrev_i32_e32 v35, 31, v34
	v_lshl_add_u64 v[34:35], v[34:35], 2, s[26:27]
	global_load_dword v0, v[34:35], off
	s_waitcnt vmcnt(0)
	v_pk_mul_f32 v[34:35], v[48:49], v[0:1] op_sel_hi:[1,0]
	v_pk_mul_f32 v[36:37], v[46:47], v[0:1] op_sel_hi:[1,0]
	v_add_u32_e32 v0, 0x840, v11
	ds_write2_b32 v0, v36, v37 offset1:1
	v_add_u32_e32 v0, 0x848, v11
	ds_write2_b32 v0, v34, v35 offset1:1
	v_or_b32_e32 v34, s34, v28
	v_ashrrev_i32_e32 v35, 31, v34
	v_lshl_add_u64 v[34:35], v[34:35], 2, s[26:27]
	global_load_dword v0, v[34:35], off
	v_add_u32_e32 v11, v21, v29
	s_waitcnt vmcnt(0)
	v_pk_mul_f32 v[34:35], v[52:53], v[0:1] op_sel_hi:[1,0]
	v_pk_mul_f32 v[36:37], v[50:51], v[0:1] op_sel_hi:[1,0]
	ds_write2_b32 v11, v36, v37 offset1:1
	ds_write2_b32 v11, v34, v35 offset0:2 offset1:3
	v_or_b32_e32 v34, s34, v30
	v_ashrrev_i32_e32 v35, 31, v34
	v_lshl_add_u64 v[34:35], v[34:35], 2, s[26:27]
	global_load_dword v0, v[34:35], off
	s_waitcnt vmcnt(0)
	v_pk_mul_f32 v[34:35], v[56:57], v[0:1] op_sel_hi:[1,0]
	v_pk_mul_f32 v[36:37], v[54:55], v[0:1] op_sel_hi:[1,0]
	v_add_u32_e32 v0, 0x420, v11
	ds_write2_b32 v0, v36, v37 offset1:1
	v_add_u32_e32 v0, 0x428, v11
	ds_write2_b32 v0, v34, v35 offset1:1
	v_or_b32_e32 v34, s34, v31
	v_ashrrev_i32_e32 v35, 31, v34
	v_lshl_add_u64 v[34:35], v[34:35], 2, s[26:27]
	global_load_dword v0, v[34:35], off
	s_waitcnt vmcnt(0)
	v_pk_mul_f32 v[8:9], v[8:9], v[0:1] op_sel_hi:[1,0]
	v_pk_mul_f32 v[6:7], v[6:7], v[0:1] op_sel_hi:[1,0]
	v_add_u32_e32 v0, 0x840, v11
	ds_write2_b32 v0, v6, v7 offset1:1
	v_or_b32_e32 v6, s34, v32
	v_ashrrev_i32_e32 v7, 31, v6
	v_add_u32_e32 v0, 0x848, v11
	v_lshl_add_u64 v[6:7], v[6:7], 2, s[26:27]
	ds_write2_b32 v0, v8, v9 offset1:1
	global_load_dword v0, v[6:7], off
	v_lshl_add_u64 v[6:7], s[34:35], 1, v[14:15]
	s_waitcnt vmcnt(0)
	v_pk_mul_f32 v[4:5], v[4:5], v[0:1] op_sel_hi:[1,0]
	v_pk_mul_f32 v[2:3], v[2:3], v[0:1] op_sel_hi:[1,0]
	v_add_u32_e32 v0, 0xc60, v11
	ds_write2_b32 v0, v2, v3 offset1:1
	v_add_u32_e32 v0, 0xc68, v11
	ds_write2_b32 v0, v4, v5 offset1:1
	s_waitcnt lgkmcnt(0)
	ds_read2_b32 v[8:9], v24 offset0:33 offset1:41
	ds_read2_b32 v[34:35], v24 offset1:8
	ds_read2_b32 v[36:37], v24 offset0:66 offset1:74
	ds_read2_b32 v[38:39], v24 offset0:99 offset1:107
	ds_read2_b32 v[40:41], v24 offset0:132 offset1:140
	ds_read2_b32 v[42:43], v24 offset0:165 offset1:173
	ds_read2_b32 v[44:45], v24 offset0:198 offset1:206
	ds_read2_b32 v[46:47], v24 offset0:231 offset1:239
	v_add_u32_e32 v11, s36, v13
	v_add_u32_e32 v0, 0xc80, v11
	v_lshlrev_b64 v[48:49], 12, v[0:1]
	s_waitcnt lgkmcnt(6)
	v_cvt_pk_bf16_f32 v2, v34, v8
	s_waitcnt lgkmcnt(4)
	v_cvt_pk_bf16_f32 v3, v36, v38
	s_waitcnt lgkmcnt(2)
	v_cvt_pk_bf16_f32 v4, v40, v42
	s_waitcnt lgkmcnt(0)
	v_cvt_pk_bf16_f32 v5, v44, v46
	v_lshl_add_u64 v[48:49], v[6:7], 0, v[48:49]
	v_add_u32_e32 v0, 0xc88, v11
	global_store_dwordx4 v[48:49], v[2:5], off
	s_nop 1
	v_cvt_pk_bf16_f32 v2, v35, v9
	v_lshlrev_b64 v[8:9], 12, v[0:1]
	v_cvt_pk_bf16_f32 v3, v37, v39
	v_cvt_pk_bf16_f32 v4, v41, v43
	v_cvt_pk_bf16_f32 v5, v45, v47
	v_lshl_add_u64 v[8:9], v[6:7], 0, v[8:9]
	global_store_dwordx4 v[8:9], v[2:5], off
	ds_read2_b32 v[8:9], v24 offset0:49 offset1:57
	ds_read2_b32 v[34:35], v24 offset0:16 offset1:24
	ds_read2_b32 v[36:37], v24 offset0:82 offset1:90
	ds_read2_b32 v[38:39], v24 offset0:115 offset1:123
	ds_read2_b32 v[40:41], v24 offset0:148 offset1:156
	ds_read2_b32 v[42:43], v24 offset0:181 offset1:189
	ds_read2_b32 v[44:45], v24 offset0:214 offset1:222
	ds_read2_b32 v[46:47], v24 offset0:247 offset1:255
	v_add_u32_e32 v0, 0xc90, v11
	v_lshlrev_b64 v[48:49], 12, v[0:1]
	s_waitcnt lgkmcnt(6)
	v_cvt_pk_bf16_f32 v2, v34, v8
	s_waitcnt lgkmcnt(4)
	v_cvt_pk_bf16_f32 v3, v36, v38
	s_waitcnt lgkmcnt(2)
	v_cvt_pk_bf16_f32 v4, v40, v42
	s_waitcnt lgkmcnt(0)
	v_cvt_pk_bf16_f32 v5, v44, v46
	v_lshl_add_u64 v[48:49], v[6:7], 0, v[48:49]
	v_add_u32_e32 v0, 0xc98, v11
	global_store_dwordx4 v[48:49], v[2:5], off
	s_nop 1
	v_cvt_pk_bf16_f32 v2, v35, v9
	v_lshlrev_b64 v[8:9], 12, v[0:1]
	v_cvt_pk_bf16_f32 v3, v37, v39
	v_cvt_pk_bf16_f32 v4, v41, v43
	v_cvt_pk_bf16_f32 v5, v45, v47
	v_lshl_add_u64 v[6:7], v[6:7], 0, v[8:9]
	global_store_dwordx4 v[6:7], v[2:5], off
	s_waitcnt lgkmcnt(0)
	s_cbranch_execnz .LBB0_1079
	s_branch .LBB0_1078

.LBB0_1087:
	s_ashr_i32 s11, s9, 31
	s_lshr_b32 s11, s11, 30
	s_add_i32 s11, s9, s11
	s_ashr_i32 s11, s11, 2
	s_lshl_b32 s18, s11, 6
	s_lshl_b32 s11, s11, 7
	s_andn2_b64 vcc, exec, s[14:15]
	s_sub_i32 s11, 0, s11
	s_cbranch_vccnz .LBB0_1089
	s_add_i32 s26, s10, s11
	v_or_b32_e32 v8, s18, v20
	s_ashr_i32 s27, s26, 31
	v_ashrrev_i32_e32 v9, 31, v8
	v_or_b32_e32 v34, 8, v8
	v_or_b32_e32 v38, 16, v8
	v_lshl_add_u64 v[18:19], s[26:27], 2, v[2:3]
	v_lshlrev_b64 v[4:5], 9, v[8:9]
	v_ashrrev_i32_e32 v35, 31, v34
	v_ashrrev_i32_e32 v39, 31, v38
	v_lshl_add_u64 v[4:5], v[18:19], 0, v[4:5]
	v_lshlrev_b64 v[34:35], 9, v[34:35]
	v_lshlrev_b64 v[38:39], 9, v[38:39]
	v_or_b32_e32 v42, 24, v8
	global_load_dwordx4 v[4:7], v[4:5], off sc0 sc1 nt
	v_lshl_add_u64 v[34:35], v[18:19], 0, v[34:35]
	v_lshl_add_u64 v[38:39], v[18:19], 0, v[38:39]
	v_ashrrev_i32_e32 v43, 31, v42
	v_or_b32_e32 v46, 32, v8
	global_load_dwordx4 v[34:37], v[34:35], off sc0 sc1 nt
	v_lshlrev_b64 v[42:43], 9, v[42:43]
	global_load_dwordx4 v[38:41], v[38:39], off sc0 sc1 nt
	v_ashrrev_i32_e32 v47, 31, v46
	v_lshl_add_u64 v[42:43], v[18:19], 0, v[42:43]
	v_lshlrev_b64 v[46:47], 9, v[46:47]
	v_or_b32_e32 v50, 40, v8
	global_load_dwordx4 v[42:45], v[42:43], off sc0 sc1 nt
	v_lshl_add_u64 v[46:47], v[18:19], 0, v[46:47]
	v_ashrrev_i32_e32 v51, 31, v50
	global_load_dwordx4 v[46:49], v[46:47], off sc0 sc1 nt
	v_lshlrev_b64 v[50:51], 9, v[50:51]
	v_or_b32_e32 v54, 48, v8
	v_lshl_add_u64 v[50:51], v[18:19], 0, v[50:51]
	v_ashrrev_i32_e32 v55, 31, v54
	global_load_dwordx4 v[50:53], v[50:51], off sc0 sc1 nt
	v_lshlrev_b64 v[54:55], 9, v[54:55]
	v_or_b32_e32 v8, 56, v8
	v_lshl_add_u64 v[54:55], v[18:19], 0, v[54:55]
	v_ashrrev_i32_e32 v9, 31, v8
	global_load_dwordx4 v[54:57], v[54:55], off sc0 sc1 nt
	v_lshlrev_b64 v[8:9], 9, v[8:9]
	v_lshl_add_u64 v[8:9], v[18:19], 0, v[8:9]
	global_load_dwordx4 v[58:61], v[8:9], off sc0 sc1 nt
	v_add_u32_e32 v0, v21, v23
	v_add_u32_e32 v11, s26, v20
	s_ashr_i32 s19, s18, 31
	s_waitcnt vmcnt(7)
	ds_write2_b32 v22, v4, v5 offset1:1
	ds_write2_b32 v22, v6, v7 offset0:2 offset1:3
	v_add_u32_e32 v4, 0x420, v0
	s_waitcnt vmcnt(6)
	ds_write2_b32 v0, v34, v35 offset1:1
	ds_write2_b32 v0, v36, v37 offset0:2 offset1:3
	s_waitcnt vmcnt(5)
	ds_write2_b32 v4, v38, v39 offset1:1
	v_add_u32_e32 v4, 0x428, v0
	ds_write2_b32 v4, v40, v41 offset1:1
	v_add_u32_e32 v4, 0x840, v0
	v_add_u32_e32 v0, 0x848, v0
	s_waitcnt vmcnt(4)
	ds_write2_b32 v0, v44, v45 offset1:1
	v_add_u32_e32 v0, 0x1080, v22
	ds_write2_b32 v4, v42, v43 offset1:1
	s_waitcnt vmcnt(3)
	ds_write2_b32 v0, v46, v47 offset1:1
	v_add_u32_e32 v0, 0x1088, v22
	ds_write2_b32 v0, v48, v49 offset1:1
	v_add_u32_e32 v0, 0x14a0, v22
	v_lshl_add_u64 v[4:5], s[18:19], 1, v[16:17]
	s_waitcnt vmcnt(2)
	ds_write2_b32 v0, v50, v51 offset1:1
	v_add_u32_e32 v0, 0x14a8, v22
	ds_write2_b32 v0, v52, v53 offset1:1
	v_add_u32_e32 v0, 0x18c0, v22
	s_waitcnt vmcnt(1)
	ds_write2_b32 v0, v54, v55 offset1:1
	v_add_u32_e32 v0, 0x18c8, v22
	ds_write2_b32 v0, v56, v57 offset1:1
	v_add_u32_e32 v0, 0x1ce0, v22
	s_waitcnt vmcnt(0)
	ds_write2_b32 v0, v58, v59 offset1:1
	v_add_u32_e32 v0, 0x1ce8, v22
	ds_write2_b32 v0, v60, v61 offset1:1
	s_waitcnt lgkmcnt(0)
	ds_read2_b32 v[18:19], v24 offset0:33 offset1:41
	ds_read2_b32 v[34:35], v24 offset1:8
	ds_read2_b32 v[36:37], v24 offset0:66 offset1:74
	ds_read2_b32 v[38:39], v24 offset0:99 offset1:107
	ds_read2_b32 v[40:41], v24 offset0:132 offset1:140
	ds_read2_b32 v[42:43], v24 offset0:165 offset1:173
	ds_read2_b32 v[44:45], v24 offset0:198 offset1:206
	ds_read2_b32 v[46:47], v24 offset0:231 offset1:239
	v_add_u32_e32 v0, 0xd00, v11
	v_lshlrev_b64 v[48:49], 12, v[0:1]
	s_waitcnt lgkmcnt(6)
	v_cvt_pk_bf16_f32 v6, v34, v18
	s_waitcnt lgkmcnt(4)
	v_cvt_pk_bf16_f32 v7, v36, v38
	s_waitcnt lgkmcnt(2)
	v_cvt_pk_bf16_f32 v8, v40, v42
	s_waitcnt lgkmcnt(0)
	v_cvt_pk_bf16_f32 v9, v44, v46
	v_lshl_add_u64 v[48:49], v[4:5], 0, v[48:49]
	v_add_u32_e32 v0, 0xd08, v11
	global_store_dwordx4 v[48:49], v[6:9], off
	s_nop 1
	v_cvt_pk_bf16_f32 v6, v35, v19
	v_lshlrev_b64 v[18:19], 12, v[0:1]
	v_cvt_pk_bf16_f32 v7, v37, v39
	v_cvt_pk_bf16_f32 v8, v41, v43
	v_cvt_pk_bf16_f32 v9, v45, v47
	v_lshl_add_u64 v[18:19], v[4:5], 0, v[18:19]
	global_store_dwordx4 v[18:19], v[6:9], off
	ds_read2_b32 v[18:19], v24 offset0:49 offset1:57
	ds_read2_b32 v[34:35], v24 offset0:16 offset1:24
	ds_read2_b32 v[36:37], v24 offset0:82 offset1:90
	ds_read2_b32 v[38:39], v24 offset0:115 offset1:123
	ds_read2_b32 v[40:41], v24 offset0:148 offset1:156
	ds_read2_b32 v[42:43], v24 offset0:181 offset1:189
	ds_read2_b32 v[44:45], v24 offset0:214 offset1:222
	ds_read2_b32 v[46:47], v24 offset0:247 offset1:255
	v_add_u32_e32 v0, 0xd10, v11
	v_lshlrev_b64 v[48:49], 12, v[0:1]
	s_waitcnt lgkmcnt(6)
	v_cvt_pk_bf16_f32 v6, v34, v18
	s_waitcnt lgkmcnt(4)
	v_cvt_pk_bf16_f32 v7, v36, v38
	s_waitcnt lgkmcnt(2)
	v_cvt_pk_bf16_f32 v8, v40, v42
	s_waitcnt lgkmcnt(0)
	v_cvt_pk_bf16_f32 v9, v44, v46
	v_lshl_add_u64 v[48:49], v[4:5], 0, v[48:49]
	v_add_u32_e32 v0, 0xd18, v11
	global_store_dwordx4 v[48:49], v[6:9], off
	s_nop 1
	v_cvt_pk_bf16_f32 v6, v35, v19
	v_lshlrev_b64 v[18:19], 12, v[0:1]
	v_cvt_pk_bf16_f32 v7, v37, v39
	v_cvt_pk_bf16_f32 v8, v41, v43
	v_cvt_pk_bf16_f32 v9, v45, v47
	v_lshl_add_u64 v[4:5], v[4:5], 0, v[18:19]
	global_store_dwordx4 v[4:5], v[6:9], off
	s_waitcnt lgkmcnt(0)
	s_cbranch_execnz .LBB0_1086
	s_branch .LBB0_1085

.LBB0_1094:
	s_ashr_i32 s11, s9, 31
	s_lshr_b32 s11, s11, 30
	s_add_i32 s11, s9, s11
	s_ashr_i32 s11, s11, 2
	s_lshl_b32 s24, s11, 6
	s_lshl_b32 s11, s11, 7
	s_andn2_b64 vcc, exec, s[18:19]
	s_sub_i32 s11, 0, s11
	s_cbranch_vccnz .LBB0_1096
	s_add_i32 s26, s10, s11
	v_or_b32_e32 v18, s24, v20
	s_ashr_i32 s27, s26, 31
	v_ashrrev_i32_e32 v19, 31, v18
	v_lshl_add_u64 v[2:3], s[26:27], 2, v[16:17]
	v_lshlrev_b64 v[4:5], 9, v[18:19]
	v_lshl_add_u64 v[4:5], v[2:3], 0, v[4:5]
	global_load_dwordx4 v[34:37], v[4:5], off sc0 sc1 nt
	v_or_b32_e32 v4, 8, v18
	v_ashrrev_i32_e32 v5, 31, v4
	v_lshlrev_b64 v[4:5], 9, v[4:5]
	v_lshl_add_u64 v[4:5], v[2:3], 0, v[4:5]
	global_load_dwordx4 v[38:41], v[4:5], off sc0 sc1 nt
	v_or_b32_e32 v4, 16, v18
	v_ashrrev_i32_e32 v5, 31, v4
	v_lshlrev_b64 v[4:5], 9, v[4:5]
	v_lshl_add_u64 v[4:5], v[2:3], 0, v[4:5]
	global_load_dwordx4 v[42:45], v[4:5], off sc0 sc1 nt
	v_or_b32_e32 v4, 24, v18
	v_ashrrev_i32_e32 v5, 31, v4
	v_lshlrev_b64 v[4:5], 9, v[4:5]
	v_lshl_add_u64 v[4:5], v[2:3], 0, v[4:5]
	global_load_dwordx4 v[46:49], v[4:5], off sc0 sc1 nt
	v_or_b32_e32 v4, 32, v18
	v_ashrrev_i32_e32 v5, 31, v4
	v_lshlrev_b64 v[4:5], 9, v[4:5]
	v_lshl_add_u64 v[4:5], v[2:3], 0, v[4:5]
	global_load_dwordx4 v[50:53], v[4:5], off sc0 sc1 nt
	v_or_b32_e32 v4, 40, v18
	v_ashrrev_i32_e32 v5, 31, v4
	v_lshlrev_b64 v[4:5], 9, v[4:5]
	v_lshl_add_u64 v[4:5], v[2:3], 0, v[4:5]
	global_load_dwordx4 v[54:57], v[4:5], off sc0 sc1 nt
	v_or_b32_e32 v4, 48, v18
	v_ashrrev_i32_e32 v5, 31, v4
	v_lshlrev_b64 v[4:5], 9, v[4:5]
	v_lshl_add_u64 v[4:5], v[2:3], 0, v[4:5]
	global_load_dwordx4 v[6:9], v[4:5], off sc0 sc1 nt
	v_or_b32_e32 v4, 56, v18
	v_lshl_add_u64 v[18:19], v[18:19], 2, s[14:15]
	global_load_dword v0, v[18:19], off
	v_ashrrev_i32_e32 v5, 31, v4
	v_lshlrev_b64 v[4:5], 9, v[4:5]
	v_lshl_add_u64 v[2:3], v[2:3], 0, v[4:5]
	global_load_dwordx4 v[2:5], v[2:3], off sc0 sc1 nt
	v_add_u32_e32 v11, v21, v23
	s_ashr_i32 s25, s24, 31
	s_waitcnt vmcnt(1)
	v_pk_mul_f32 v[18:19], v[36:37], v[0:1] op_sel_hi:[1,0]
	v_pk_mul_f32 v[34:35], v[34:35], v[0:1] op_sel_hi:[1,0]
	ds_write2_b32 v22, v34, v35 offset1:1
	ds_write2_b32 v22, v18, v19 offset0:2 offset1:3
	v_or_b32_e32 v18, s24, v26
	v_ashrrev_i32_e32 v19, 31, v18
	v_lshl_add_u64 v[18:19], v[18:19], 2, s[14:15]
	global_load_dword v0, v[18:19], off
	s_waitcnt vmcnt(0)
	v_pk_mul_f32 v[18:19], v[40:41], v[0:1] op_sel_hi:[1,0]
	v_pk_mul_f32 v[34:35], v[38:39], v[0:1] op_sel_hi:[1,0]
	ds_write2_b32 v11, v34, v35 offset1:1
	ds_write2_b32 v11, v18, v19 offset0:2 offset1:3
	v_or_b32_e32 v18, s24, v27
	v_ashrrev_i32_e32 v19, 31, v18
	v_lshl_add_u64 v[18:19], v[18:19], 2, s[14:15]
	global_load_dword v0, v[18:19], off
	s_waitcnt vmcnt(0)
	v_pk_mul_f32 v[18:19], v[44:45], v[0:1] op_sel_hi:[1,0]
	v_pk_mul_f32 v[34:35], v[42:43], v[0:1] op_sel_hi:[1,0]
	v_add_u32_e32 v0, 0x420, v11
	ds_write2_b32 v0, v34, v35 offset1:1
	v_add_u32_e32 v0, 0x428, v11
	ds_write2_b32 v0, v18, v19 offset1:1
	v_or_b32_e32 v18, s24, v25
	v_ashrrev_i32_e32 v19, 31, v18
	v_lshl_add_u64 v[18:19], v[18:19], 2, s[14:15]
	global_load_dword v0, v[18:19], off
	s_waitcnt vmcnt(0)
	v_pk_mul_f32 v[18:19], v[48:49], v[0:1] op_sel_hi:[1,0]
	v_pk_mul_f32 v[34:35], v[46:47], v[0:1] op_sel_hi:[1,0]
	v_add_u32_e32 v0, 0x840, v11
	ds_write2_b32 v0, v34, v35 offset1:1
	v_add_u32_e32 v0, 0x848, v11
	ds_write2_b32 v0, v18, v19 offset1:1
	v_or_b32_e32 v18, s24, v28
	v_ashrrev_i32_e32 v19, 31, v18
	v_lshl_add_u64 v[18:19], v[18:19], 2, s[14:15]
	global_load_dword v0, v[18:19], off
	v_add_u32_e32 v11, v21, v29
	s_waitcnt vmcnt(0)
	v_pk_mul_f32 v[18:19], v[52:53], v[0:1] op_sel_hi:[1,0]
	v_pk_mul_f32 v[34:35], v[50:51], v[0:1] op_sel_hi:[1,0]
	ds_write2_b32 v11, v34, v35 offset1:1
	ds_write2_b32 v11, v18, v19 offset0:2 offset1:3
	v_or_b32_e32 v18, s24, v30
	v_ashrrev_i32_e32 v19, 31, v18
	v_lshl_add_u64 v[18:19], v[18:19], 2, s[14:15]
	global_load_dword v0, v[18:19], off
	s_waitcnt vmcnt(0)
	v_pk_mul_f32 v[18:19], v[56:57], v[0:1] op_sel_hi:[1,0]
	v_pk_mul_f32 v[34:35], v[54:55], v[0:1] op_sel_hi:[1,0]
	v_add_u32_e32 v0, 0x420, v11
	ds_write2_b32 v0, v34, v35 offset1:1
	v_add_u32_e32 v0, 0x428, v11
	ds_write2_b32 v0, v18, v19 offset1:1
	v_or_b32_e32 v18, s24, v31
	v_ashrrev_i32_e32 v19, 31, v18
	v_lshl_add_u64 v[18:19], v[18:19], 2, s[14:15]
	global_load_dword v0, v[18:19], off
	s_waitcnt vmcnt(0)
	v_pk_mul_f32 v[8:9], v[8:9], v[0:1] op_sel_hi:[1,0]
	v_pk_mul_f32 v[6:7], v[6:7], v[0:1] op_sel_hi:[1,0]
	v_add_u32_e32 v0, 0x840, v11
	ds_write2_b32 v0, v6, v7 offset1:1
	v_or_b32_e32 v6, s24, v32
	v_ashrrev_i32_e32 v7, 31, v6
	v_add_u32_e32 v0, 0x848, v11
	v_lshl_add_u64 v[6:7], v[6:7], 2, s[14:15]
	ds_write2_b32 v0, v8, v9 offset1:1
	global_load_dword v0, v[6:7], off
	v_lshl_add_u64 v[6:7], s[24:25], 1, v[14:15]
	s_waitcnt vmcnt(0)
	v_pk_mul_f32 v[4:5], v[4:5], v[0:1] op_sel_hi:[1,0]
	v_pk_mul_f32 v[2:3], v[2:3], v[0:1] op_sel_hi:[1,0]
	v_add_u32_e32 v0, 0xc60, v11
	ds_write2_b32 v0, v2, v3 offset1:1
	v_add_u32_e32 v0, 0xc68, v11
	ds_write2_b32 v0, v4, v5 offset1:1
	s_waitcnt lgkmcnt(0)
	ds_read2_b32 v[8:9], v24 offset0:33 offset1:41
	ds_read2_b32 v[18:19], v24 offset1:8
	ds_read2_b32 v[34:35], v24 offset0:66 offset1:74
	ds_read2_b32 v[36:37], v24 offset0:99 offset1:107
	ds_read2_b32 v[38:39], v24 offset0:132 offset1:140
	ds_read2_b32 v[40:41], v24 offset0:165 offset1:173
	ds_read2_b32 v[42:43], v24 offset0:198 offset1:206
	ds_read2_b32 v[44:45], v24 offset0:231 offset1:239
	v_add_u32_e32 v11, s26, v20
	v_add_u32_e32 v0, 0xd00, v11
	v_lshlrev_b64 v[46:47], 12, v[0:1]
	s_waitcnt lgkmcnt(6)
	v_cvt_pk_bf16_f32 v2, v18, v8
	s_waitcnt lgkmcnt(4)
	v_cvt_pk_bf16_f32 v3, v34, v36
	s_waitcnt lgkmcnt(2)
	v_cvt_pk_bf16_f32 v4, v38, v40
	s_waitcnt lgkmcnt(0)
	v_cvt_pk_bf16_f32 v5, v42, v44
	v_lshl_add_u64 v[46:47], v[6:7], 0, v[46:47]
	v_add_u32_e32 v0, 0xd08, v11
	global_store_dwordx4 v[46:47], v[2:5], off
	s_nop 1
	v_cvt_pk_bf16_f32 v2, v19, v9
	v_lshlrev_b64 v[8:9], 12, v[0:1]
	v_cvt_pk_bf16_f32 v3, v35, v37
	v_cvt_pk_bf16_f32 v4, v39, v41
	v_cvt_pk_bf16_f32 v5, v43, v45
	v_lshl_add_u64 v[8:9], v[6:7], 0, v[8:9]
	global_store_dwordx4 v[8:9], v[2:5], off
	ds_read2_b32 v[8:9], v24 offset0:49 offset1:57
	ds_read2_b32 v[18:19], v24 offset0:16 offset1:24
	ds_read2_b32 v[34:35], v24 offset0:82 offset1:90
	ds_read2_b32 v[36:37], v24 offset0:115 offset1:123
	ds_read2_b32 v[38:39], v24 offset0:148 offset1:156
	ds_read2_b32 v[40:41], v24 offset0:181 offset1:189
	ds_read2_b32 v[42:43], v24 offset0:214 offset1:222
	ds_read2_b32 v[44:45], v24 offset0:247 offset1:255
	v_add_u32_e32 v0, 0xd10, v11
	v_lshlrev_b64 v[46:47], 12, v[0:1]
	s_waitcnt lgkmcnt(6)
	v_cvt_pk_bf16_f32 v2, v18, v8
	s_waitcnt lgkmcnt(4)
	v_cvt_pk_bf16_f32 v3, v34, v36
	s_waitcnt lgkmcnt(2)
	v_cvt_pk_bf16_f32 v4, v38, v40
	s_waitcnt lgkmcnt(0)
	v_cvt_pk_bf16_f32 v5, v42, v44
	v_lshl_add_u64 v[46:47], v[6:7], 0, v[46:47]
	v_add_u32_e32 v0, 0xd18, v11
	global_store_dwordx4 v[46:47], v[2:5], off
	s_nop 1
	v_cvt_pk_bf16_f32 v2, v19, v9
	v_lshlrev_b64 v[8:9], 12, v[0:1]
	v_cvt_pk_bf16_f32 v3, v35, v37
	v_cvt_pk_bf16_f32 v4, v39, v41
	v_cvt_pk_bf16_f32 v5, v43, v45
	v_lshl_add_u64 v[6:7], v[6:7], 0, v[8:9]
	global_store_dwordx4 v[6:7], v[2:5], off
	s_waitcnt lgkmcnt(0)
	s_cbranch_execnz .LBB0_1093
	s_branch .LBB0_1092

.LBB0_1116:
	s_ashr_i32 s14, s22, 31
	s_lshr_b32 s14, s14, 27
	s_add_i32 s14, s22, s14
	s_ashr_i32 s15, s14, 5
	s_lshl_b32 s14, s15, 6
	s_lshl_b32 s15, s15, 10
	s_andn2_b64 vcc, exec, s[6:7]
	s_sub_i32 s24, 0, s15
	s_cbranch_vccnz .LBB0_1118
	v_or_b32_e32 v50, s14, v20
	s_add_i32 s18, s23, s24
	v_or_b32_e32 v26, 8, v50
	v_or_b32_e32 v30, 16, v50
	s_ashr_i32 s19, s18, 31
	v_ashrrev_i32_e32 v51, 31, v50
	v_ashrrev_i32_e32 v27, 31, v26
	v_ashrrev_i32_e32 v31, 31, v30
	v_lshl_add_u64 v[52:53], s[18:19], 2, v[14:15]
	v_lshlrev_b64 v[16:17], 12, v[50:51]
	v_lshlrev_b64 v[26:27], 12, v[26:27]
	v_lshlrev_b64 v[30:31], 12, v[30:31]
	v_or_b32_e32 v34, 24, v50
	v_lshl_add_u64 v[16:17], v[52:53], 0, v[16:17]
	v_lshl_add_u64 v[26:27], v[52:53], 0, v[26:27]
	v_lshl_add_u64 v[30:31], v[52:53], 0, v[30:31]
	v_ashrrev_i32_e32 v35, 31, v34
	v_or_b32_e32 v38, 32, v50
	global_load_dwordx4 v[16:19], v[16:17], off sc0 sc1 nt
	v_lshlrev_b64 v[34:35], 12, v[34:35]
	global_load_dwordx4 v[26:29], v[26:27], off sc0 sc1 nt
	v_ashrrev_i32_e32 v39, 31, v38
	global_load_dwordx4 v[30:33], v[30:31], off sc0 sc1 nt
	v_lshl_add_u64 v[34:35], v[52:53], 0, v[34:35]
	v_lshlrev_b64 v[38:39], 12, v[38:39]
	v_or_b32_e32 v42, 40, v50
	global_load_dwordx4 v[34:37], v[34:35], off sc0 sc1 nt
	v_lshl_add_u64 v[38:39], v[52:53], 0, v[38:39]
	v_ashrrev_i32_e32 v43, 31, v42
	global_load_dwordx4 v[38:41], v[38:39], off sc0 sc1 nt
	v_lshlrev_b64 v[42:43], 12, v[42:43]
	v_or_b32_e32 v46, 48, v50
	v_lshl_add_u64 v[42:43], v[52:53], 0, v[42:43]
	v_ashrrev_i32_e32 v47, 31, v46
	global_load_dwordx4 v[42:45], v[42:43], off sc0 sc1 nt
	v_lshlrev_b64 v[46:47], 12, v[46:47]
	v_or_b32_e32 v50, 56, v50
	v_lshl_add_u64 v[46:47], v[52:53], 0, v[46:47]
	v_ashrrev_i32_e32 v51, 31, v50
	global_load_dwordx4 v[46:49], v[46:47], off sc0 sc1 nt
	v_lshlrev_b64 v[50:51], 12, v[50:51]
	v_lshl_add_u64 v[50:51], v[52:53], 0, v[50:51]
	global_load_dwordx4 v[50:53], v[50:51], off sc0 sc1 nt
	v_add_u32_e32 v11, v21, v23
	v_add_u32_e32 v13, 0x420, v11
	s_ashr_i32 s15, s14, 31
	s_waitcnt vmcnt(7)
	ds_write2_b32 v22, v16, v17 offset1:1
	ds_write2_b32 v22, v18, v19 offset0:2 offset1:3
	s_waitcnt vmcnt(6)
	ds_write2_b32 v11, v26, v27 offset1:1
	ds_write2_b32 v11, v28, v29 offset0:2 offset1:3
	v_lshl_add_u64 v[16:17], s[14:15], 1, v[8:9]
	s_waitcnt vmcnt(5)
	ds_write2_b32 v13, v30, v31 offset1:1
	v_add_u32_e32 v13, 0x428, v11
	ds_write2_b32 v13, v32, v33 offset1:1
	v_add_u32_e32 v13, 0x840, v11
	v_add_u32_e32 v11, 0x848, v11
	s_waitcnt vmcnt(4)
	ds_write2_b32 v11, v36, v37 offset1:1
	v_add_u32_e32 v11, 0x1080, v22
	s_waitcnt vmcnt(3)
	ds_write2_b32 v11, v38, v39 offset1:1
	v_add_u32_e32 v11, 0x1088, v22
	ds_write2_b32 v11, v40, v41 offset1:1
	v_add_u32_e32 v11, 0x14a0, v22
	ds_write2_b32 v13, v34, v35 offset1:1
	s_waitcnt vmcnt(2)
	ds_write2_b32 v11, v42, v43 offset1:1
	v_add_u32_e32 v11, 0x14a8, v22
	ds_write2_b32 v11, v44, v45 offset1:1
	v_add_u32_e32 v11, 0x18c0, v22
	v_add_u32_e32 v44, s18, v0
	s_waitcnt vmcnt(1)
	ds_write2_b32 v11, v46, v47 offset1:1
	v_add_u32_e32 v11, 0x18c8, v22
	ds_write2_b32 v11, v48, v49 offset1:1
	v_add_u32_e32 v11, 0x1ce0, v22
	s_waitcnt vmcnt(0)
	ds_write2_b32 v11, v50, v51 offset1:1
	v_add_u32_e32 v11, 0x1ce8, v22
	ds_write2_b32 v11, v52, v53 offset1:1
	s_waitcnt lgkmcnt(0)
	ds_read2_b32 v[18:19], v24 offset0:33 offset1:41
	ds_read2_b32 v[30:31], v24 offset1:8
	ds_read2_b32 v[32:33], v24 offset0:66 offset1:74
	ds_read2_b32 v[34:35], v24 offset0:99 offset1:107
	ds_read2_b32 v[36:37], v24 offset0:132 offset1:140
	ds_read2_b32 v[38:39], v24 offset0:165 offset1:173
	ds_read2_b32 v[40:41], v24 offset0:198 offset1:206
	ds_read2_b32 v[42:43], v24 offset0:231 offset1:239
	v_ashrrev_i32_e32 v45, 31, v44
	v_lshlrev_b64 v[46:47], 9, v[44:45]
	s_waitcnt lgkmcnt(6)
	v_cvt_pk_bf16_f32 v26, v30, v18
	s_waitcnt lgkmcnt(4)
	v_cvt_pk_bf16_f32 v27, v32, v34
	s_waitcnt lgkmcnt(2)
	v_cvt_pk_bf16_f32 v28, v36, v38
	s_waitcnt lgkmcnt(0)
	v_cvt_pk_bf16_f32 v29, v40, v42
	v_lshl_add_u64 v[46:47], v[16:17], 0, v[46:47]
	v_add_u32_e32 v18, 8, v44
	global_store_dwordx4 v[46:47], v[26:29], off
	v_add_u32_e32 v46, 16, v44
	v_ashrrev_i32_e32 v47, 31, v46
	v_cvt_pk_bf16_f32 v26, v31, v19
	v_ashrrev_i32_e32 v19, 31, v18
	v_lshlrev_b64 v[18:19], 9, v[18:19]
	v_cvt_pk_bf16_f32 v27, v33, v35
	v_cvt_pk_bf16_f32 v28, v37, v39
	v_cvt_pk_bf16_f32 v29, v41, v43
	v_lshl_add_u64 v[18:19], v[16:17], 0, v[18:19]
	global_store_dwordx4 v[18:19], v[26:29], off
	ds_read2_b32 v[18:19], v24 offset0:49 offset1:57
	ds_read2_b32 v[30:31], v24 offset0:16 offset1:24
	ds_read2_b32 v[32:33], v24 offset0:82 offset1:90
	ds_read2_b32 v[34:35], v24 offset0:115 offset1:123
	ds_read2_b32 v[36:37], v24 offset0:148 offset1:156
	ds_read2_b32 v[38:39], v24 offset0:181 offset1:189
	ds_read2_b32 v[40:41], v24 offset0:214 offset1:222
	ds_read2_b32 v[42:43], v24 offset0:247 offset1:255
	v_lshlrev_b64 v[46:47], 9, v[46:47]
	s_waitcnt lgkmcnt(6)
	v_cvt_pk_bf16_f32 v26, v30, v18
	s_waitcnt lgkmcnt(4)
	v_cvt_pk_bf16_f32 v27, v32, v34
	s_waitcnt lgkmcnt(2)
	v_cvt_pk_bf16_f32 v28, v36, v38
	s_waitcnt lgkmcnt(0)
	v_cvt_pk_bf16_f32 v29, v40, v42
	v_lshl_add_u64 v[46:47], v[16:17], 0, v[46:47]
	v_add_u32_e32 v18, 24, v44
	global_store_dwordx4 v[46:47], v[26:29], off
	s_nop 1
	v_cvt_pk_bf16_f32 v26, v31, v19
	v_ashrrev_i32_e32 v19, 31, v18
	v_lshlrev_b64 v[18:19], 9, v[18:19]
	v_cvt_pk_bf16_f32 v27, v33, v35
	v_cvt_pk_bf16_f32 v28, v37, v39
	v_cvt_pk_bf16_f32 v29, v41, v43
	v_lshl_add_u64 v[16:17], v[16:17], 0, v[18:19]
	global_store_dwordx4 v[16:17], v[26:29], off
	s_waitcnt lgkmcnt(0)
	s_cbranch_execnz .LBB0_1115
	s_branch .LBB0_1114

.LBB0_1123:
	s_ashr_i32 s12, s10, 31
	s_lshr_b32 s12, s12, 27
	s_add_i32 s12, s10, s12
	s_ashr_i32 s12, s12, 5
	s_lshl_b32 s14, s12, 6
	s_lshl_b32 s12, s12, 10
	s_andn2_b64 vcc, exec, s[6:7]
	s_sub_i32 s12, 0, s12
	s_cbranch_vccnz .LBB0_1125
	v_or_b32_e32 v8, s14, v20
	s_add_i32 s18, s11, s12
	v_or_b32_e32 v26, 8, v8
	v_or_b32_e32 v30, 16, v8
	s_ashr_i32 s19, s18, 31
	v_ashrrev_i32_e32 v9, 31, v8
	v_ashrrev_i32_e32 v27, 31, v26
	v_ashrrev_i32_e32 v31, 31, v30
	v_lshl_add_u64 v[18:19], s[18:19], 2, v[4:5]
	v_lshlrev_b64 v[14:15], 12, v[8:9]
	v_lshlrev_b64 v[26:27], 12, v[26:27]
	v_lshlrev_b64 v[30:31], 12, v[30:31]
	v_or_b32_e32 v34, 24, v8
	v_lshl_add_u64 v[14:15], v[18:19], 0, v[14:15]
	v_lshl_add_u64 v[26:27], v[18:19], 0, v[26:27]
	v_lshl_add_u64 v[30:31], v[18:19], 0, v[30:31]
	v_ashrrev_i32_e32 v35, 31, v34
	v_or_b32_e32 v38, 32, v8
	global_load_dwordx4 v[14:17], v[14:15], off sc0 sc1 nt
	v_lshlrev_b64 v[34:35], 12, v[34:35]
	global_load_dwordx4 v[26:29], v[26:27], off sc0 sc1 nt
	v_ashrrev_i32_e32 v39, 31, v38
	global_load_dwordx4 v[30:33], v[30:31], off sc0 sc1 nt
	v_lshl_add_u64 v[34:35], v[18:19], 0, v[34:35]
	v_lshlrev_b64 v[38:39], 12, v[38:39]
	v_or_b32_e32 v42, 40, v8
	global_load_dwordx4 v[34:37], v[34:35], off sc0 sc1 nt
	v_lshl_add_u64 v[38:39], v[18:19], 0, v[38:39]
	v_ashrrev_i32_e32 v43, 31, v42
	global_load_dwordx4 v[38:41], v[38:39], off sc0 sc1 nt
	v_lshlrev_b64 v[42:43], 12, v[42:43]
	v_or_b32_e32 v46, 48, v8
	v_lshl_add_u64 v[42:43], v[18:19], 0, v[42:43]
	v_ashrrev_i32_e32 v47, 31, v46
	global_load_dwordx4 v[42:45], v[42:43], off sc0 sc1 nt
	v_lshlrev_b64 v[46:47], 12, v[46:47]
	v_or_b32_e32 v8, 56, v8
	v_lshl_add_u64 v[46:47], v[18:19], 0, v[46:47]
	v_ashrrev_i32_e32 v9, 31, v8
	global_load_dwordx4 v[46:49], v[46:47], off sc0 sc1 nt
	v_lshlrev_b64 v[8:9], 12, v[8:9]
	v_lshl_add_u64 v[8:9], v[18:19], 0, v[8:9]
	global_load_dwordx4 v[50:53], v[8:9], off sc0 sc1 nt
	v_add_u32_e32 v0, v21, v23
	v_add_u32_e32 v8, 0x420, v0
	s_ashr_i32 s15, s14, 31
	s_waitcnt vmcnt(7)
	ds_write2_b32 v22, v14, v15 offset1:1
	ds_write2_b32 v22, v16, v17 offset0:2 offset1:3
	s_waitcnt vmcnt(6)
	ds_write2_b32 v0, v26, v27 offset1:1
	ds_write2_b32 v0, v28, v29 offset0:2 offset1:3
	s_waitcnt vmcnt(5)
	ds_write2_b32 v8, v30, v31 offset1:1
	v_add_u32_e32 v8, 0x428, v0
	ds_write2_b32 v8, v32, v33 offset1:1
	v_add_u32_e32 v8, 0x840, v0
	v_add_u32_e32 v0, 0x848, v0
	s_waitcnt vmcnt(4)
	ds_write2_b32 v0, v36, v37 offset1:1
	v_add_u32_e32 v0, 0x1080, v22
	s_waitcnt vmcnt(3)
	ds_write2_b32 v0, v38, v39 offset1:1
	v_add_u32_e32 v0, 0x1088, v22
	ds_write2_b32 v0, v40, v41 offset1:1
	v_add_u32_e32 v0, 0x14a0, v22
	ds_write2_b32 v8, v34, v35 offset1:1
	s_waitcnt vmcnt(2)
	ds_write2_b32 v0, v42, v43 offset1:1
	v_add_u32_e32 v0, 0x14a8, v22
	ds_write2_b32 v0, v44, v45 offset1:1
	v_add_u32_e32 v0, 0x18c0, v22
	v_add_u32_e32 v40, s18, v20
	s_waitcnt vmcnt(1)
	ds_write2_b32 v0, v46, v47 offset1:1
	v_add_u32_e32 v0, 0x18c8, v22
	ds_write2_b32 v0, v48, v49 offset1:1
	v_add_u32_e32 v0, 0x1ce0, v22
	s_waitcnt vmcnt(0)
	ds_write2_b32 v0, v50, v51 offset1:1
	v_add_u32_e32 v0, 0x1ce8, v22
	ds_write2_b32 v0, v52, v53 offset1:1
	s_waitcnt lgkmcnt(0)
	ds_read2_b32 v[18:19], v24 offset0:33 offset1:41
	ds_read2_b32 v[26:27], v24 offset1:8
	ds_read2_b32 v[28:29], v24 offset0:66 offset1:74
	ds_read2_b32 v[30:31], v24 offset0:99 offset1:107
	ds_read2_b32 v[32:33], v24 offset0:132 offset1:140
	ds_read2_b32 v[34:35], v24 offset0:165 offset1:173
	ds_read2_b32 v[36:37], v24 offset0:198 offset1:206
	ds_read2_b32 v[38:39], v24 offset0:231 offset1:239
	v_ashrrev_i32_e32 v41, 31, v40
	v_lshl_add_u64 v[8:9], s[14:15], 1, v[6:7]
	v_lshlrev_b64 v[42:43], 9, v[40:41]
	s_waitcnt lgkmcnt(6)
	v_cvt_pk_bf16_f32 v14, v26, v18
	s_waitcnt lgkmcnt(4)
	v_cvt_pk_bf16_f32 v15, v28, v30
	s_waitcnt lgkmcnt(2)
	v_cvt_pk_bf16_f32 v16, v32, v34
	s_waitcnt lgkmcnt(0)
	v_cvt_pk_bf16_f32 v17, v36, v38
	v_lshl_add_u64 v[42:43], v[8:9], 0, v[42:43]
	v_add_u32_e32 v18, 8, v40
	global_store_dwordx4 v[42:43], v[14:17], off
	v_add_u32_e32 v42, 16, v40
	v_ashrrev_i32_e32 v43, 31, v42
	v_cvt_pk_bf16_f32 v14, v27, v19
	v_ashrrev_i32_e32 v19, 31, v18
	v_lshlrev_b64 v[18:19], 9, v[18:19]
	v_cvt_pk_bf16_f32 v15, v29, v31
	v_cvt_pk_bf16_f32 v16, v33, v35
	v_cvt_pk_bf16_f32 v17, v37, v39
	v_lshl_add_u64 v[18:19], v[8:9], 0, v[18:19]
	global_store_dwordx4 v[18:19], v[14:17], off
	ds_read2_b32 v[18:19], v24 offset0:49 offset1:57
	ds_read2_b32 v[26:27], v24 offset0:16 offset1:24
	ds_read2_b32 v[28:29], v24 offset0:82 offset1:90
	ds_read2_b32 v[30:31], v24 offset0:115 offset1:123
	ds_read2_b32 v[32:33], v24 offset0:148 offset1:156
	ds_read2_b32 v[34:35], v24 offset0:181 offset1:189
	ds_read2_b32 v[36:37], v24 offset0:214 offset1:222
	ds_read2_b32 v[38:39], v24 offset0:247 offset1:255
	v_lshlrev_b64 v[42:43], 9, v[42:43]
	s_waitcnt lgkmcnt(6)
	v_cvt_pk_bf16_f32 v14, v26, v18
	s_waitcnt lgkmcnt(4)
	v_cvt_pk_bf16_f32 v15, v28, v30
	s_waitcnt lgkmcnt(2)
	v_cvt_pk_bf16_f32 v16, v32, v34
	s_waitcnt lgkmcnt(0)
	v_cvt_pk_bf16_f32 v17, v36, v38
	v_lshl_add_u64 v[42:43], v[8:9], 0, v[42:43]
	v_add_u32_e32 v18, 24, v40
	global_store_dwordx4 v[42:43], v[14:17], off
	s_nop 1
	v_cvt_pk_bf16_f32 v14, v27, v19
	v_ashrrev_i32_e32 v19, 31, v18
	v_lshlrev_b64 v[18:19], 9, v[18:19]
	v_cvt_pk_bf16_f32 v15, v29, v31
	v_cvt_pk_bf16_f32 v16, v33, v35
	v_cvt_pk_bf16_f32 v17, v37, v39
	v_lshl_add_u64 v[8:9], v[8:9], 0, v[18:19]
	global_store_dwordx4 v[8:9], v[14:17], off
	s_waitcnt lgkmcnt(0)
	s_cbranch_execnz .LBB0_1122
	s_branch .LBB0_1121

.LBB0_1132:
	s_ashr_i32 s10, s8, 31
	s_lshr_b32 s10, s10, 27
	s_add_i32 s10, s8, s10
	s_ashr_i32 s10, s10, 5
	s_lshl_b32 s14, s10, 6
	s_lshl_b32 s10, s10, 10
	s_andn2_b64 vcc, exec, s[6:7]
	s_sub_i32 s10, 0, s10
	s_cbranch_vccnz .LBB0_1134
	s_add_i32 s18, s9, s10
	v_or_b32_e32 v18, s14, v20
	s_ashr_i32 s19, s18, 31
	v_ashrrev_i32_e32 v19, 31, v18
	v_or_b32_e32 v14, 8, v18
	v_or_b32_e32 v26, 16, v18
	v_lshl_add_u64 v[46:47], s[18:19], 2, v[2:3]
	v_lshlrev_b64 v[6:7], 12, v[18:19]
	v_ashrrev_i32_e32 v15, 31, v14
	v_ashrrev_i32_e32 v27, 31, v26
	v_lshl_add_u64 v[6:7], v[46:47], 0, v[6:7]
	v_lshlrev_b64 v[14:15], 12, v[14:15]
	v_lshlrev_b64 v[26:27], 12, v[26:27]
	v_or_b32_e32 v30, 24, v18
	global_load_dwordx4 v[6:9], v[6:7], off sc0 sc1 nt
	v_lshl_add_u64 v[14:15], v[46:47], 0, v[14:15]
	v_lshl_add_u64 v[26:27], v[46:47], 0, v[26:27]
	v_ashrrev_i32_e32 v31, 31, v30
	v_or_b32_e32 v34, 32, v18
	global_load_dwordx4 v[14:17], v[14:15], off sc0 sc1 nt
	v_lshlrev_b64 v[30:31], 12, v[30:31]
	global_load_dwordx4 v[26:29], v[26:27], off sc0 sc1 nt
	v_ashrrev_i32_e32 v35, 31, v34
	v_lshl_add_u64 v[30:31], v[46:47], 0, v[30:31]
	v_lshlrev_b64 v[34:35], 12, v[34:35]
	v_or_b32_e32 v38, 40, v18
	global_load_dwordx4 v[30:33], v[30:31], off sc0 sc1 nt
	v_lshl_add_u64 v[34:35], v[46:47], 0, v[34:35]
	v_ashrrev_i32_e32 v39, 31, v38
	global_load_dwordx4 v[34:37], v[34:35], off sc0 sc1 nt
	v_lshlrev_b64 v[38:39], 12, v[38:39]
	v_or_b32_e32 v42, 48, v18
	v_lshl_add_u64 v[38:39], v[46:47], 0, v[38:39]
	v_ashrrev_i32_e32 v43, 31, v42
	global_load_dwordx4 v[38:41], v[38:39], off sc0 sc1 nt
	v_lshlrev_b64 v[42:43], 12, v[42:43]
	v_or_b32_e32 v18, 56, v18
	v_lshl_add_u64 v[42:43], v[46:47], 0, v[42:43]
	v_ashrrev_i32_e32 v19, 31, v18
	global_load_dwordx4 v[42:45], v[42:43], off sc0 sc1 nt
	v_lshlrev_b64 v[18:19], 12, v[18:19]
	v_lshl_add_u64 v[18:19], v[46:47], 0, v[18:19]
	global_load_dwordx4 v[46:49], v[18:19], off sc0 sc1 nt
	v_add_u32_e32 v0, v21, v23
	s_ashr_i32 s15, s14, 31
	s_waitcnt vmcnt(7)
	ds_write2_b32 v22, v6, v7 offset1:1
	ds_write2_b32 v22, v8, v9 offset0:2 offset1:3
	v_add_u32_e32 v6, 0x420, v0
	s_waitcnt vmcnt(6)
	ds_write2_b32 v0, v14, v15 offset1:1
	ds_write2_b32 v0, v16, v17 offset0:2 offset1:3
	s_waitcnt vmcnt(5)
	ds_write2_b32 v6, v26, v27 offset1:1
	v_add_u32_e32 v6, 0x428, v0
	ds_write2_b32 v6, v28, v29 offset1:1
	v_add_u32_e32 v6, 0x840, v0
	v_add_u32_e32 v0, 0x848, v0
	s_waitcnt vmcnt(4)
	ds_write2_b32 v0, v32, v33 offset1:1
	v_add_u32_e32 v0, 0x1080, v22
	ds_write2_b32 v6, v30, v31 offset1:1
	s_waitcnt vmcnt(3)
	ds_write2_b32 v0, v34, v35 offset1:1
	v_add_u32_e32 v0, 0x1088, v22
	ds_write2_b32 v0, v36, v37 offset1:1
	v_add_u32_e32 v0, 0x14a0, v22
	v_lshl_add_u64 v[6:7], s[14:15], 1, v[4:5]
	s_waitcnt vmcnt(2)
	ds_write2_b32 v0, v38, v39 offset1:1
	v_add_u32_e32 v0, 0x14a8, v22
	ds_write2_b32 v0, v40, v41 offset1:1
	v_add_u32_e32 v0, 0x18c0, v22
	v_add_u32_e32 v38, s18, v20
	s_waitcnt vmcnt(1)
	ds_write2_b32 v0, v42, v43 offset1:1
	v_add_u32_e32 v0, 0x18c8, v22
	ds_write2_b32 v0, v44, v45 offset1:1
	v_add_u32_e32 v0, 0x1ce0, v22
	s_waitcnt vmcnt(0)
	ds_write2_b32 v0, v46, v47 offset1:1
	v_add_u32_e32 v0, 0x1ce8, v22
	ds_write2_b32 v0, v48, v49 offset1:1
	s_waitcnt lgkmcnt(0)
	ds_read2_b32 v[8:9], v24 offset0:33 offset1:41
	ds_read2_b32 v[18:19], v24 offset1:8
	ds_read2_b32 v[26:27], v24 offset0:66 offset1:74
	ds_read2_b32 v[28:29], v24 offset0:99 offset1:107
	ds_read2_b32 v[30:31], v24 offset0:132 offset1:140
	ds_read2_b32 v[32:33], v24 offset0:165 offset1:173
	ds_read2_b32 v[34:35], v24 offset0:198 offset1:206
	ds_read2_b32 v[36:37], v24 offset0:231 offset1:239
	v_ashrrev_i32_e32 v39, 31, v38
	v_lshlrev_b64 v[40:41], 11, v[38:39]
	s_waitcnt lgkmcnt(6)
	v_cvt_pk_bf16_f32 v14, v18, v8
	s_waitcnt lgkmcnt(4)
	v_cvt_pk_bf16_f32 v15, v26, v28
	s_waitcnt lgkmcnt(2)
	v_cvt_pk_bf16_f32 v16, v30, v32
	s_waitcnt lgkmcnt(0)
	v_cvt_pk_bf16_f32 v17, v34, v36
	v_lshl_add_u64 v[40:41], v[6:7], 0, v[40:41]
	v_add_u32_e32 v8, 8, v38
	global_store_dwordx4 v[40:41], v[14:17], off
	v_add_u32_e32 v40, 16, v38
	v_ashrrev_i32_e32 v41, 31, v40
	v_cvt_pk_bf16_f32 v14, v19, v9
	v_ashrrev_i32_e32 v9, 31, v8
	v_lshlrev_b64 v[8:9], 11, v[8:9]
	v_cvt_pk_bf16_f32 v15, v27, v29
	v_cvt_pk_bf16_f32 v16, v31, v33
	v_cvt_pk_bf16_f32 v17, v35, v37
	v_lshl_add_u64 v[8:9], v[6:7], 0, v[8:9]
	global_store_dwordx4 v[8:9], v[14:17], off
	ds_read2_b32 v[8:9], v24 offset0:49 offset1:57
	ds_read2_b32 v[18:19], v24 offset0:16 offset1:24
	ds_read2_b32 v[26:27], v24 offset0:82 offset1:90
	ds_read2_b32 v[28:29], v24 offset0:115 offset1:123
	ds_read2_b32 v[30:31], v24 offset0:148 offset1:156
	ds_read2_b32 v[32:33], v24 offset0:181 offset1:189
	ds_read2_b32 v[34:35], v24 offset0:214 offset1:222
	ds_read2_b32 v[36:37], v24 offset0:247 offset1:255
	v_lshlrev_b64 v[40:41], 11, v[40:41]
	s_waitcnt lgkmcnt(6)
	v_cvt_pk_bf16_f32 v14, v18, v8
	s_waitcnt lgkmcnt(4)
	v_cvt_pk_bf16_f32 v15, v26, v28
	s_waitcnt lgkmcnt(2)
	v_cvt_pk_bf16_f32 v16, v30, v32
	s_waitcnt lgkmcnt(0)
	v_cvt_pk_bf16_f32 v17, v34, v36
	v_lshl_add_u64 v[40:41], v[6:7], 0, v[40:41]
	v_add_u32_e32 v8, 24, v38
	global_store_dwordx4 v[40:41], v[14:17], off
	s_nop 1
	v_cvt_pk_bf16_f32 v14, v19, v9
	v_ashrrev_i32_e32 v9, 31, v8
	v_lshlrev_b64 v[8:9], 11, v[8:9]
	v_cvt_pk_bf16_f32 v15, v27, v29
	v_cvt_pk_bf16_f32 v16, v31, v33
	v_cvt_pk_bf16_f32 v17, v35, v37
	v_lshl_add_u64 v[6:7], v[6:7], 0, v[8:9]
	global_store_dwordx4 v[6:7], v[14:17], off
	s_waitcnt lgkmcnt(0)
	s_cbranch_execnz .LBB0_1131
	s_branch .LBB0_1130

.LBB0_1139:
	s_mul_hi_i32 s10, s9, 0x2aaaaaab
	s_lshr_b32 s11, s10, 31
	s_ashr_i32 s10, s10, 4
	s_add_i32 s10, s10, s11
	s_lshl_b32 s14, s10, 6
	s_andn2_b64 vcc, exec, s[6:7]
	s_mulk_i32 s10, 0xf400
	s_cbranch_vccnz .LBB0_1141
	s_add_i32 s18, s8, s10
	v_or_b32_e32 v0, s14, v20
	s_ashr_i32 s19, s18, 31
	v_lshl_add_u64 v[18:19], s[18:19], 2, v[2:3]
	s_movk_i32 s11, 0x3000
	v_or_b32_e32 v11, 8, v0
	v_mad_i64_i32 v[6:7], s[12:13], v0, s11, v[18:19]
	v_mad_i64_i32 v[14:15], s[12:13], v11, s11, v[18:19]
	v_or_b32_e32 v11, 16, v0
	global_load_dwordx4 v[6:9], v[6:7], off sc0 sc1 nt
	v_mad_i64_i32 v[26:27], s[12:13], v11, s11, v[18:19]
	global_load_dwordx4 v[14:17], v[14:15], off sc0 sc1 nt
	v_or_b32_e32 v11, 24, v0
	global_load_dwordx4 v[26:29], v[26:27], off sc0 sc1 nt
	v_mad_i64_i32 v[30:31], s[12:13], v11, s11, v[18:19]
	v_or_b32_e32 v11, 32, v0
	global_load_dwordx4 v[30:33], v[30:31], off sc0 sc1 nt
	v_mad_i64_i32 v[34:35], s[12:13], v11, s11, v[18:19]
	global_load_dwordx4 v[34:37], v[34:35], off sc0 sc1 nt
	v_or_b32_e32 v11, 40, v0
	v_mad_i64_i32 v[38:39], s[12:13], v11, s11, v[18:19]
	global_load_dwordx4 v[38:41], v[38:39], off sc0 sc1 nt
	v_or_b32_e32 v11, 48, v0
	v_mad_i64_i32 v[42:43], s[12:13], v11, s11, v[18:19]
	global_load_dwordx4 v[42:45], v[42:43], off sc0 sc1 nt
	v_or_b32_e32 v0, 56, v0
	v_mad_i64_i32 v[18:19], s[12:13], v0, s11, v[18:19]
	global_load_dwordx4 v[46:49], v[18:19], off sc0 sc1 nt
	v_add_u32_e32 v0, v21, v23
	s_ashr_i32 s15, s14, 31
	s_waitcnt vmcnt(7)
	ds_write2_b32 v22, v6, v7 offset1:1
	ds_write2_b32 v22, v8, v9 offset0:2 offset1:3
	v_add_u32_e32 v6, 0x420, v0
	s_waitcnt vmcnt(6)
	ds_write2_b32 v0, v14, v15 offset1:1
	ds_write2_b32 v0, v16, v17 offset0:2 offset1:3
	v_add_u32_e32 v8, s18, v20
	s_waitcnt vmcnt(5)
	ds_write2_b32 v6, v26, v27 offset1:1
	v_add_u32_e32 v6, 0x428, v0
	ds_write2_b32 v6, v28, v29 offset1:1
	v_add_u32_e32 v6, 0x840, v0
	v_add_u32_e32 v0, 0x848, v0
	s_waitcnt vmcnt(4)
	ds_write2_b32 v0, v32, v33 offset1:1
	v_add_u32_e32 v0, 0x1080, v22
	s_waitcnt vmcnt(3)
	ds_write2_b32 v0, v34, v35 offset1:1
	v_add_u32_e32 v0, 0x1088, v22
	ds_write2_b32 v0, v36, v37 offset1:1
	v_add_u32_e32 v0, 0x14a0, v22
	s_waitcnt vmcnt(2)
	ds_write2_b32 v0, v38, v39 offset1:1
	v_add_u32_e32 v0, 0x14a8, v22
	ds_write2_b32 v0, v40, v41 offset1:1
	v_add_u32_e32 v0, 0x18c0, v22
	s_waitcnt vmcnt(1)
	ds_write2_b32 v0, v42, v43 offset1:1
	v_add_u32_e32 v0, 0x18c8, v22
	ds_write2_b32 v0, v44, v45 offset1:1
	v_add_u32_e32 v0, 0x1ce0, v22
	s_waitcnt vmcnt(0)
	ds_write2_b32 v0, v46, v47 offset1:1
	v_add_u32_e32 v0, 0x1ce8, v22
	ds_write2_b32 v6, v30, v31 offset1:1
	ds_write2_b32 v0, v48, v49 offset1:1
	s_waitcnt lgkmcnt(0)
	ds_read2_b32 v[18:19], v24 offset0:33 offset1:41
	ds_read2_b32 v[26:27], v24 offset1:8
	ds_read2_b32 v[28:29], v24 offset0:66 offset1:74
	ds_read2_b32 v[30:31], v24 offset0:99 offset1:107
	ds_read2_b32 v[32:33], v24 offset0:132 offset1:140
	ds_read2_b32 v[34:35], v24 offset0:165 offset1:173
	ds_read2_b32 v[36:37], v24 offset0:198 offset1:206
	ds_read2_b32 v[38:39], v24 offset0:231 offset1:239
	v_ashrrev_i32_e32 v9, 31, v8
	v_lshl_add_u64 v[6:7], s[14:15], 1, v[4:5]
	v_lshlrev_b64 v[40:41], 11, v[8:9]
	s_waitcnt lgkmcnt(6)
	v_cvt_pk_bf16_f32 v14, v26, v18
	s_waitcnt lgkmcnt(4)
	v_cvt_pk_bf16_f32 v15, v28, v30
	s_waitcnt lgkmcnt(2)
	v_cvt_pk_bf16_f32 v16, v32, v34
	s_waitcnt lgkmcnt(0)
	v_cvt_pk_bf16_f32 v17, v36, v38
	v_lshl_add_u64 v[40:41], v[6:7], 0, v[40:41]
	v_add_u32_e32 v18, 8, v8
	global_store_dwordx4 v[40:41], v[14:17], off
	v_add_u32_e32 v40, 16, v8
	v_ashrrev_i32_e32 v41, 31, v40
	v_cvt_pk_bf16_f32 v14, v27, v19
	v_ashrrev_i32_e32 v19, 31, v18
	v_lshlrev_b64 v[18:19], 11, v[18:19]
	v_cvt_pk_bf16_f32 v15, v29, v31
	v_cvt_pk_bf16_f32 v16, v33, v35
	v_cvt_pk_bf16_f32 v17, v37, v39
	v_lshl_add_u64 v[18:19], v[6:7], 0, v[18:19]
	global_store_dwordx4 v[18:19], v[14:17], off
	ds_read2_b32 v[18:19], v24 offset0:49 offset1:57
	ds_read2_b32 v[26:27], v24 offset0:16 offset1:24
	ds_read2_b32 v[28:29], v24 offset0:82 offset1:90
	ds_read2_b32 v[30:31], v24 offset0:115 offset1:123
	ds_read2_b32 v[32:33], v24 offset0:148 offset1:156
	ds_read2_b32 v[34:35], v24 offset0:181 offset1:189
	ds_read2_b32 v[36:37], v24 offset0:214 offset1:222
	ds_read2_b32 v[38:39], v24 offset0:247 offset1:255
	v_add_u32_e32 v8, 24, v8
	v_lshlrev_b64 v[40:41], 11, v[40:41]
	v_ashrrev_i32_e32 v9, 31, v8
	s_waitcnt lgkmcnt(6)
	v_cvt_pk_bf16_f32 v14, v26, v18
	s_waitcnt lgkmcnt(4)
	v_cvt_pk_bf16_f32 v15, v28, v30
	s_waitcnt lgkmcnt(2)
	v_cvt_pk_bf16_f32 v16, v32, v34
	s_waitcnt lgkmcnt(0)
	v_cvt_pk_bf16_f32 v17, v36, v38
	v_lshl_add_u64 v[40:41], v[6:7], 0, v[40:41]
	v_lshlrev_b64 v[8:9], 11, v[8:9]
	global_store_dwordx4 v[40:41], v[14:17], off
	v_lshl_add_u64 v[6:7], v[6:7], 0, v[8:9]
	s_nop 0
	v_cvt_pk_bf16_f32 v14, v27, v19
	v_cvt_pk_bf16_f32 v15, v29, v31
	v_cvt_pk_bf16_f32 v16, v33, v35
	v_cvt_pk_bf16_f32 v17, v37, v39
	global_store_dwordx4 v[6:7], v[14:17], off
	s_waitcnt lgkmcnt(0)
	s_cbranch_execnz .LBB0_1138
	s_branch .LBB0_1137

.LBB0_1145:
	s_ashr_i32 s9, s8, 31
	s_lshr_b32 s9, s9, 27
	s_add_i32 s9, s8, s9
	s_ashr_i32 s9, s9, 5
	s_lshl_b32 s14, s9, 6
	s_lshl_b32 s9, s9, 10
	s_andn2_b64 vcc, exec, s[6:7]
	s_sub_i32 s9, 0, s9
	s_cbranch_vccnz .LBB0_1147
	s_add_i32 s18, s5, s9
	v_or_b32_e32 v18, s14, v20
	s_ashr_i32 s19, s18, 31
	v_ashrrev_i32_e32 v19, 31, v18
	v_or_b32_e32 v14, 8, v18
	v_or_b32_e32 v26, 16, v18
	v_lshl_add_u64 v[46:47], s[18:19], 2, v[2:3]
	v_lshlrev_b64 v[6:7], 12, v[18:19]
	v_ashrrev_i32_e32 v15, 31, v14
	v_ashrrev_i32_e32 v27, 31, v26
	v_lshl_add_u64 v[6:7], v[46:47], 0, v[6:7]
	v_lshlrev_b64 v[14:15], 12, v[14:15]
	v_lshlrev_b64 v[26:27], 12, v[26:27]
	v_or_b32_e32 v30, 24, v18
	global_load_dwordx4 v[6:9], v[6:7], off sc0 sc1 nt
	v_lshl_add_u64 v[14:15], v[46:47], 0, v[14:15]
	v_lshl_add_u64 v[26:27], v[46:47], 0, v[26:27]
	v_ashrrev_i32_e32 v31, 31, v30
	v_or_b32_e32 v34, 32, v18
	global_load_dwordx4 v[14:17], v[14:15], off sc0 sc1 nt
	v_lshlrev_b64 v[30:31], 12, v[30:31]
	global_load_dwordx4 v[26:29], v[26:27], off sc0 sc1 nt
	v_ashrrev_i32_e32 v35, 31, v34
	v_lshl_add_u64 v[30:31], v[46:47], 0, v[30:31]
	v_lshlrev_b64 v[34:35], 12, v[34:35]
	v_or_b32_e32 v38, 40, v18
	global_load_dwordx4 v[30:33], v[30:31], off sc0 sc1 nt
	v_lshl_add_u64 v[34:35], v[46:47], 0, v[34:35]
	v_ashrrev_i32_e32 v39, 31, v38
	global_load_dwordx4 v[34:37], v[34:35], off sc0 sc1 nt
	v_lshlrev_b64 v[38:39], 12, v[38:39]
	v_or_b32_e32 v42, 48, v18
	v_lshl_add_u64 v[38:39], v[46:47], 0, v[38:39]
	v_ashrrev_i32_e32 v43, 31, v42
	global_load_dwordx4 v[38:41], v[38:39], off sc0 sc1 nt
	v_lshlrev_b64 v[42:43], 12, v[42:43]
	v_or_b32_e32 v18, 56, v18
	v_lshl_add_u64 v[42:43], v[46:47], 0, v[42:43]
	v_ashrrev_i32_e32 v19, 31, v18
	global_load_dwordx4 v[42:45], v[42:43], off sc0 sc1 nt
	v_lshlrev_b64 v[18:19], 12, v[18:19]
	v_lshl_add_u64 v[18:19], v[46:47], 0, v[18:19]
	global_load_dwordx4 v[46:49], v[18:19], off sc0 sc1 nt
	v_add_u32_e32 v0, v21, v23
	s_ashr_i32 s15, s14, 31
	s_waitcnt vmcnt(7)
	ds_write2_b32 v22, v6, v7 offset1:1
	ds_write2_b32 v22, v8, v9 offset0:2 offset1:3
	v_add_u32_e32 v6, 0x420, v0
	s_waitcnt vmcnt(6)
	ds_write2_b32 v0, v14, v15 offset1:1
	ds_write2_b32 v0, v16, v17 offset0:2 offset1:3
	s_waitcnt vmcnt(5)
	ds_write2_b32 v6, v26, v27 offset1:1
	v_add_u32_e32 v6, 0x428, v0
	ds_write2_b32 v6, v28, v29 offset1:1
	v_add_u32_e32 v6, 0x840, v0
	v_add_u32_e32 v0, 0x848, v0
	s_waitcnt vmcnt(4)
	ds_write2_b32 v0, v32, v33 offset1:1
	v_add_u32_e32 v0, 0x1080, v22
	ds_write2_b32 v6, v30, v31 offset1:1
	s_waitcnt vmcnt(3)
	ds_write2_b32 v0, v34, v35 offset1:1
	v_add_u32_e32 v0, 0x1088, v22
	ds_write2_b32 v0, v36, v37 offset1:1
	v_add_u32_e32 v0, 0x14a0, v22
	v_lshl_add_u64 v[6:7], s[14:15], 1, v[4:5]
	s_waitcnt vmcnt(2)
	ds_write2_b32 v0, v38, v39 offset1:1
	v_add_u32_e32 v0, 0x14a8, v22
	ds_write2_b32 v0, v40, v41 offset1:1
	v_add_u32_e32 v0, 0x18c0, v22
	v_add_u32_e32 v38, s18, v20
	s_waitcnt vmcnt(1)
	ds_write2_b32 v0, v42, v43 offset1:1
	v_add_u32_e32 v0, 0x18c8, v22
	ds_write2_b32 v0, v44, v45 offset1:1
	v_add_u32_e32 v0, 0x1ce0, v22
	s_waitcnt vmcnt(0)
	ds_write2_b32 v0, v46, v47 offset1:1
	v_add_u32_e32 v0, 0x1ce8, v22
	ds_write2_b32 v0, v48, v49 offset1:1
	s_waitcnt lgkmcnt(0)
	ds_read2_b32 v[8:9], v24 offset0:33 offset1:41
	ds_read2_b32 v[18:19], v24 offset1:8
	ds_read2_b32 v[26:27], v24 offset0:66 offset1:74
	ds_read2_b32 v[28:29], v24 offset0:99 offset1:107
	ds_read2_b32 v[30:31], v24 offset0:132 offset1:140
	ds_read2_b32 v[32:33], v24 offset0:165 offset1:173
	ds_read2_b32 v[34:35], v24 offset0:198 offset1:206
	ds_read2_b32 v[36:37], v24 offset0:231 offset1:239
	v_ashrrev_i32_e32 v39, 31, v38
	v_lshlrev_b64 v[40:41], 11, v[38:39]
	s_waitcnt lgkmcnt(6)
	v_cvt_pk_bf16_f32 v14, v18, v8
	s_waitcnt lgkmcnt(4)
	v_cvt_pk_bf16_f32 v15, v26, v28
	s_waitcnt lgkmcnt(2)
	v_cvt_pk_bf16_f32 v16, v30, v32
	s_waitcnt lgkmcnt(0)
	v_cvt_pk_bf16_f32 v17, v34, v36
	v_lshl_add_u64 v[40:41], v[6:7], 0, v[40:41]
	v_add_u32_e32 v8, 8, v38
	global_store_dwordx4 v[40:41], v[14:17], off
	v_add_u32_e32 v40, 16, v38
	v_ashrrev_i32_e32 v41, 31, v40
	v_cvt_pk_bf16_f32 v14, v19, v9
	v_ashrrev_i32_e32 v9, 31, v8
	v_lshlrev_b64 v[8:9], 11, v[8:9]
	v_cvt_pk_bf16_f32 v15, v27, v29
	v_cvt_pk_bf16_f32 v16, v31, v33
	v_cvt_pk_bf16_f32 v17, v35, v37
	v_lshl_add_u64 v[8:9], v[6:7], 0, v[8:9]
	global_store_dwordx4 v[8:9], v[14:17], off
	ds_read2_b32 v[8:9], v24 offset0:49 offset1:57
	ds_read2_b32 v[18:19], v24 offset0:16 offset1:24
	ds_read2_b32 v[26:27], v24 offset0:82 offset1:90
	ds_read2_b32 v[28:29], v24 offset0:115 offset1:123
	ds_read2_b32 v[30:31], v24 offset0:148 offset1:156
	ds_read2_b32 v[32:33], v24 offset0:181 offset1:189
	ds_read2_b32 v[34:35], v24 offset0:214 offset1:222
	ds_read2_b32 v[36:37], v24 offset0:247 offset1:255
	v_lshlrev_b64 v[40:41], 11, v[40:41]
	s_waitcnt lgkmcnt(6)
	v_cvt_pk_bf16_f32 v14, v18, v8
	s_waitcnt lgkmcnt(4)
	v_cvt_pk_bf16_f32 v15, v26, v28
	s_waitcnt lgkmcnt(2)
	v_cvt_pk_bf16_f32 v16, v30, v32
	s_waitcnt lgkmcnt(0)
	v_cvt_pk_bf16_f32 v17, v34, v36
	v_lshl_add_u64 v[40:41], v[6:7], 0, v[40:41]
	v_add_u32_e32 v8, 24, v38
	global_store_dwordx4 v[40:41], v[14:17], off
	s_nop 1
	v_cvt_pk_bf16_f32 v14, v19, v9
	v_ashrrev_i32_e32 v9, 31, v8
	v_lshlrev_b64 v[8:9], 11, v[8:9]
	v_cvt_pk_bf16_f32 v15, v27, v29
	v_cvt_pk_bf16_f32 v16, v31, v33
	v_cvt_pk_bf16_f32 v17, v35, v37
	v_lshl_add_u64 v[6:7], v[6:7], 0, v[8:9]
	global_store_dwordx4 v[6:7], v[14:17], off
	s_waitcnt lgkmcnt(0)
	s_cbranch_execnz .LBB0_1144
	s_branch .LBB0_1143

.LBB0_1153:
	s_ashr_i32 s6, s3, 31
	s_lshr_b32 s6, s6, 25
	s_add_i32 s6, s3, s6
	s_ashr_i32 s7, s6, 7
	s_lshl_b32 s6, s7, 6
	s_lshl_b32 s7, s7, 12
	s_andn2_b64 vcc, exec, s[0:1]
	s_sub_i32 s8, 0, s7
	s_cbranch_vccnz .LBB0_1155
	s_add_i32 s14, s5, s8
	v_or_b32_e32 v18, s6, v20
	s_ashr_i32 s15, s14, 31
	v_ashrrev_i32_e32 v19, 31, v18
	v_or_b32_e32 v10, 8, v18
	v_or_b32_e32 v14, 16, v18
	v_lshl_add_u64 v[42:43], s[14:15], 2, v[2:3]
	v_lshlrev_b64 v[6:7], 14, v[18:19]
	v_ashrrev_i32_e32 v11, 31, v10
	v_ashrrev_i32_e32 v15, 31, v14
	v_lshl_add_u64 v[6:7], v[42:43], 0, v[6:7]
	v_lshlrev_b64 v[10:11], 14, v[10:11]
	v_lshlrev_b64 v[14:15], 14, v[14:15]
	v_or_b32_e32 v26, 24, v18
	global_load_dwordx4 v[6:9], v[6:7], off sc0 sc1 nt
	v_lshl_add_u64 v[10:11], v[42:43], 0, v[10:11]
	v_lshl_add_u64 v[14:15], v[42:43], 0, v[14:15]
	v_ashrrev_i32_e32 v27, 31, v26
	v_or_b32_e32 v30, 32, v18
	global_load_dwordx4 v[10:13], v[10:11], off sc0 sc1 nt
	v_lshlrev_b64 v[26:27], 14, v[26:27]
	global_load_dwordx4 v[14:17], v[14:15], off sc0 sc1 nt
	v_ashrrev_i32_e32 v31, 31, v30
	v_lshl_add_u64 v[26:27], v[42:43], 0, v[26:27]
	v_lshlrev_b64 v[30:31], 14, v[30:31]
	v_or_b32_e32 v34, 40, v18
	global_load_dwordx4 v[26:29], v[26:27], off sc0 sc1 nt
	v_lshl_add_u64 v[30:31], v[42:43], 0, v[30:31]
	v_ashrrev_i32_e32 v35, 31, v34
	global_load_dwordx4 v[30:33], v[30:31], off sc0 sc1 nt
	v_lshlrev_b64 v[34:35], 14, v[34:35]
	v_or_b32_e32 v38, 48, v18
	v_lshl_add_u64 v[34:35], v[42:43], 0, v[34:35]
	v_ashrrev_i32_e32 v39, 31, v38
	global_load_dwordx4 v[34:37], v[34:35], off sc0 sc1 nt
	v_lshlrev_b64 v[38:39], 14, v[38:39]
	v_or_b32_e32 v18, 56, v18
	v_lshl_add_u64 v[38:39], v[42:43], 0, v[38:39]
	v_ashrrev_i32_e32 v19, 31, v18
	global_load_dwordx4 v[38:41], v[38:39], off sc0 sc1 nt
	v_lshlrev_b64 v[18:19], 14, v[18:19]
	v_lshl_add_u64 v[18:19], v[42:43], 0, v[18:19]
	global_load_dwordx4 v[42:45], v[18:19], off sc0 sc1 nt
	v_add_u32_e32 v0, v21, v23
	s_ashr_i32 s7, s6, 31
	s_waitcnt vmcnt(7)
	ds_write2_b32 v22, v6, v7 offset1:1
	ds_write2_b32 v22, v8, v9 offset0:2 offset1:3
	v_add_u32_e32 v6, 0x420, v0
	s_waitcnt vmcnt(6)
	ds_write2_b32 v0, v10, v11 offset1:1
	ds_write2_b32 v0, v12, v13 offset0:2 offset1:3
	s_waitcnt vmcnt(5)
	ds_write2_b32 v6, v14, v15 offset1:1
	v_add_u32_e32 v6, 0x428, v0
	ds_write2_b32 v6, v16, v17 offset1:1
	v_add_u32_e32 v6, 0x840, v0
	v_add_u32_e32 v0, 0x848, v0
	s_waitcnt vmcnt(4)
	ds_write2_b32 v0, v28, v29 offset1:1
	v_add_u32_e32 v0, 0x1080, v22
	ds_write2_b32 v6, v26, v27 offset1:1
	s_waitcnt vmcnt(3)
	ds_write2_b32 v0, v30, v31 offset1:1
	v_add_u32_e32 v0, 0x1088, v22
	ds_write2_b32 v0, v32, v33 offset1:1
	v_add_u32_e32 v0, 0x14a0, v22
	v_lshl_add_u64 v[6:7], s[6:7], 1, v[4:5]
	s_waitcnt vmcnt(2)
	ds_write2_b32 v0, v34, v35 offset1:1
	v_add_u32_e32 v0, 0x14a8, v22
	ds_write2_b32 v0, v36, v37 offset1:1
	v_add_u32_e32 v0, 0x18c0, v22
	v_add_u32_e32 v34, s14, v20
	s_waitcnt vmcnt(1)
	ds_write2_b32 v0, v38, v39 offset1:1
	v_add_u32_e32 v0, 0x18c8, v22
	ds_write2_b32 v0, v40, v41 offset1:1
	v_add_u32_e32 v0, 0x1ce0, v22
	s_waitcnt vmcnt(0)
	ds_write2_b32 v0, v42, v43 offset1:1
	v_add_u32_e32 v0, 0x1ce8, v22
	ds_write2_b32 v0, v44, v45 offset1:1
	s_waitcnt lgkmcnt(0)
	ds_read2_b32 v[12:13], v24 offset0:33 offset1:41
	ds_read2_b32 v[14:15], v24 offset1:8
	ds_read2_b32 v[16:17], v24 offset0:66 offset1:74
	ds_read2_b32 v[18:19], v24 offset0:99 offset1:107
	ds_read2_b32 v[26:27], v24 offset0:132 offset1:140
	ds_read2_b32 v[28:29], v24 offset0:165 offset1:173
	ds_read2_b32 v[30:31], v24 offset0:198 offset1:206
	ds_read2_b32 v[32:33], v24 offset0:231 offset1:239
	v_ashrrev_i32_e32 v35, 31, v34
	v_lshlrev_b64 v[36:37], 11, v[34:35]
	s_waitcnt lgkmcnt(6)
	v_cvt_pk_bf16_f32 v8, v14, v12
	s_waitcnt lgkmcnt(4)
	v_cvt_pk_bf16_f32 v9, v16, v18
	s_waitcnt lgkmcnt(2)
	v_cvt_pk_bf16_f32 v10, v26, v28
	s_waitcnt lgkmcnt(0)
	v_cvt_pk_bf16_f32 v11, v30, v32
	v_lshl_add_u64 v[36:37], v[6:7], 0, v[36:37]
	v_add_u32_e32 v12, 8, v34
	global_store_dwordx4 v[36:37], v[8:11], off
	v_add_u32_e32 v36, 16, v34
	v_ashrrev_i32_e32 v37, 31, v36
	v_cvt_pk_bf16_f32 v8, v15, v13
	v_ashrrev_i32_e32 v13, 31, v12
	v_lshlrev_b64 v[12:13], 11, v[12:13]
	v_cvt_pk_bf16_f32 v9, v17, v19
	v_cvt_pk_bf16_f32 v10, v27, v29
	v_cvt_pk_bf16_f32 v11, v31, v33
	v_lshl_add_u64 v[12:13], v[6:7], 0, v[12:13]
	global_store_dwordx4 v[12:13], v[8:11], off
	ds_read2_b32 v[12:13], v24 offset0:49 offset1:57
	ds_read2_b32 v[14:15], v24 offset0:16 offset1:24
	ds_read2_b32 v[16:17], v24 offset0:82 offset1:90
	ds_read2_b32 v[18:19], v24 offset0:115 offset1:123
	ds_read2_b32 v[26:27], v24 offset0:148 offset1:156
	ds_read2_b32 v[28:29], v24 offset0:181 offset1:189
	ds_read2_b32 v[30:31], v24 offset0:214 offset1:222
	ds_read2_b32 v[32:33], v24 offset0:247 offset1:255
	v_lshlrev_b64 v[36:37], 11, v[36:37]
	s_waitcnt lgkmcnt(6)
	v_cvt_pk_bf16_f32 v8, v14, v12
	s_waitcnt lgkmcnt(4)
	v_cvt_pk_bf16_f32 v9, v16, v18
	s_waitcnt lgkmcnt(2)
	v_cvt_pk_bf16_f32 v10, v26, v28
	s_waitcnt lgkmcnt(0)
	v_cvt_pk_bf16_f32 v11, v30, v32
	v_lshl_add_u64 v[36:37], v[6:7], 0, v[36:37]
	v_add_u32_e32 v12, 24, v34
	global_store_dwordx4 v[36:37], v[8:11], off
	s_nop 1
	v_cvt_pk_bf16_f32 v8, v15, v13
	v_ashrrev_i32_e32 v13, 31, v12
	v_lshlrev_b64 v[12:13], 11, v[12:13]
	v_cvt_pk_bf16_f32 v9, v17, v19
	v_cvt_pk_bf16_f32 v10, v27, v29
	v_cvt_pk_bf16_f32 v11, v31, v33
	v_lshl_add_u64 v[6:7], v[6:7], 0, v[12:13]
	global_store_dwordx4 v[6:7], v[8:11], off
	s_waitcnt lgkmcnt(0)
	s_cbranch_execnz .LBB0_1152
	s_branch .LBB0_1151
